# GEMM K-loops: all s_setprio flips removed (A/B against the LDS-DMA version)
# speedup vs baseline: 1.0054x; 1.0008x over previous
; #define PG8_STAGE(bufoff, gbase, voff) do { _Pragma("unroll") for (int _i = 0; _i < 2; ++_i) \
;         __builtin_amdgcn_global_load_lds((const unsigned*)((const char*)(gbase) + (voff)[_i]), (PG8_LAS unsigned*)(lds + (bufoff) + ldsw + _i * 8192), 16, 0, 0); } while (0)
; #define PG8_LDA(dst, b, h) do { _Pragma("unroll") for (int m = 0; m < 4; ++m) _Pragma("unroll") for (int k = 0; k < 2; ++k) dst[m][k] = *(const PG8_LAS bf16x8*)(lds + PG8_SA(b, h) + aoff + m * 2048 + k * 1024); } while (0)
; #define PG8_LDB(dst, b, h) do { _Pragma("unroll") for (int n = 0; n < 2; ++n) _Pragma("unroll") for (int k = 0; k < 2; ++k) dst[n][k] = *(const PG8_LAS bf16x8*)(lds + PG8_SB(b, h) + boff + n * 2048 + k * 1024); } while (0)
; #define PG8_MMA(ai, bj, At, Bt) do { __builtin_amdgcn_s_setprio(1); _Pragma("unroll") for (int m = 0; m < 4; ++m) _Pragma("unroll") for (int n = 0; n < 2; ++n) _Pragma("unroll") for (int k = 0; k < 2; ++k) \
;         acc[ai][bj][m][n] = __builtin_amdgcn_mfma_f32_16x16x32_bf16(Bt[n][k], At[m][k], acc[ai][bj][m][n], 0, 0, 0); __builtin_amdgcn_s_setprio(0); } while (0)
; #define PG8_WAIT_V(n) asm volatile("s_waitcnt vmcnt(" #n ")" ::: "memory")
; #define PG8_WAIT_L(n) asm volatile("s_waitcnt lgkmcnt(" #n ")" ::: "memory")
; template <class Epi, class Sched, bool ALIGN_EPI = false, bool SP2 = false>
; __device__ __forceinline__ void gemm_phase(PG8_LAS unsigned char* lds, const Gemm g, const Sched& S, const Epi& E) {
;     ...
;             const bool last = (t == nt - 2);
;             const char* a1 = cA + (size_t)(t + 1) * kstep;
;             const char* a2 = last ? nA : cA + (size_t)(t + 2) * kstep; const char* b2 = last ? nB : cB + (size_t)(t + 2) * kstep;
;             const char* a3 = a2 + kstep; const char* b3 = b2 + kstep;
;             if (last && has_next) S.a_ready(nxt);
;             if constexpr (SP2) {
;             PG8_LDB(B0, 0, 0); PG8_LDB(B1, 0, 1); PG8_SCHED; PG8_LDA(At, 0, 0); PG8_STAGE(PG8_SA(1, 1), a1 + hstepA, voffA);
;             PG8_WAIT_V(8); PG8_WAIT_L(0); PG8_BAR; PG8_MMA(0, 0, At, B0); PG8_MMA(0, 1, At, B1); PG8_BAR; PG8_SCHED;
;             PG8_LDA(At, 0, 1); PG8_STAGE(PG8_SB(0, 0), b2, voffB); PG8_STAGE(PG8_SB(0, 1), b2 + hstep, voffB); PG8_STAGE(PG8_SA(0, 0), a2, voffA);
;             PG8_WAIT_V(8); PG8_WAIT_L(0); PG8_BAR; PG8_MMA(1, 0, At, B0); PG8_MMA(1, 1, At, B1); PG8_BAR; PG8_SCHED;
.LBB0_231:
	s_add_u32 s34, s42, 0xfffc0080
	s_addc_u32 s35, s43, -1
	s_add_i32 s62, 0, 0x10000
	s_cmp_eq_u32 s61, 4
	s_cselect_b32 s47, s37, s35
	s_cselect_b32 s46, s57, s34
	v_add_u32_e32 v145, s62, v142
	s_cselect_b32 s45, s27, s60
	s_cselect_b32 s44, s58, s59
	s_add_i32 s63, 0, 0x14000
	ds_read_b128 v[146:149], v145
	ds_read_b128 v[150:153], v145 offset:1024
	ds_read_b128 v[154:157], v145 offset:2048
	ds_read_b128 v[158:161], v145 offset:3072
	v_add_u32_e32 v145, s63, v142
	ds_read_b128 v[162:165], v145
	ds_read_b128 v[166:169], v145 offset:1024
	ds_read_b128 v[170:173], v145 offset:2048
	ds_read_b128 v[174:177], v145 offset:3072
	v_lshl_add_u64 v[210:211], s[42:43], 0, v[138:139]
	s_add_i32 m0, s7, 0xc000
	ds_read_b128 v[178:181], v144
	ds_read_b128 v[182:185], v144 offset:1024
	ds_read_b128 v[186:189], v144 offset:2048
	ds_read_b128 v[190:193], v144 offset:3072
	ds_read_b128 v[194:197], v144 offset:4096
	ds_read_b128 v[198:201], v144 offset:5120
	ds_read_b128 v[202:205], v144 offset:6144
	ds_read_b128 v[206:209], v144 offset:7168
	global_load_lds_dwordx4 v[210:211], off
	v_lshl_add_u64 v[210:211], s[42:43], 0, v[140:141]
	s_add_i32 m0, s7, 0xe000
	s_nop 0
	global_load_lds_dwordx4 v[210:211], off
	s_waitcnt vmcnt(8)
	s_waitcnt lgkmcnt(0)
	s_barrier
	s_waitcnt lgkmcnt(0)
	v_mfma_f32_16x16x32_bf16 v[126:129], v[146:149], v[178:181], v[126:129]
	v_mfma_f32_16x16x32_bf16 v[122:125], v[154:157], v[178:181], v[122:125]
	v_mfma_f32_16x16x32_bf16 v[118:121], v[146:149], v[186:189], v[118:121]
	v_mfma_f32_16x16x32_bf16 v[114:117], v[154:157], v[186:189], v[114:117]
	v_mfma_f32_16x16x32_bf16 v[102:105], v[146:149], v[194:197], v[102:105]
	v_mfma_f32_16x16x32_bf16 v[98:101], v[154:157], v[194:197], v[98:101]
	v_mfma_f32_16x16x32_bf16 v[86:89], v[146:149], v[202:205], v[86:89]
	v_mfma_f32_16x16x32_bf16 v[82:85], v[154:157], v[202:205], v[82:85]
	v_mfma_f32_16x16x32_bf16 v[126:129], v[150:153], v[182:185], v[126:129]
	v_mfma_f32_16x16x32_bf16 v[122:125], v[158:161], v[182:185], v[122:125]
	v_mfma_f32_16x16x32_bf16 v[118:121], v[150:153], v[190:193], v[118:121]
	v_mfma_f32_16x16x32_bf16 v[114:117], v[158:161], v[190:193], v[114:117]
	v_mfma_f32_16x16x32_bf16 v[102:105], v[150:153], v[198:201], v[102:105]
	v_mfma_f32_16x16x32_bf16 v[98:101], v[158:161], v[198:201], v[98:101]
	v_mfma_f32_16x16x32_bf16 v[86:89], v[150:153], v[206:209], v[86:89]
	v_mfma_f32_16x16x32_bf16 v[82:85], v[158:161], v[206:209], v[82:85]
	v_mfma_f32_16x16x32_bf16 v[110:113], v[162:165], v[178:181], v[110:113]
	v_mfma_f32_16x16x32_bf16 v[106:109], v[170:173], v[178:181], v[106:109]
	v_mfma_f32_16x16x32_bf16 v[94:97], v[162:165], v[186:189], v[94:97]
	v_mfma_f32_16x16x32_bf16 v[90:93], v[170:173], v[186:189], v[90:93]
	v_mfma_f32_16x16x32_bf16 v[78:81], v[162:165], v[194:197], v[78:81]
	v_mfma_f32_16x16x32_bf16 v[74:77], v[170:173], v[194:197], v[74:77]
	v_mfma_f32_16x16x32_bf16 v[70:73], v[162:165], v[202:205], v[70:73]
	v_mfma_f32_16x16x32_bf16 v[66:69], v[170:173], v[202:205], v[66:69]
	v_mfma_f32_16x16x32_bf16 v[110:113], v[166:169], v[182:185], v[110:113]
	v_mfma_f32_16x16x32_bf16 v[106:109], v[174:177], v[182:185], v[106:109]
	v_mfma_f32_16x16x32_bf16 v[94:97], v[166:169], v[190:193], v[94:97]
	v_mfma_f32_16x16x32_bf16 v[90:93], v[174:177], v[190:193], v[90:93]
	v_mfma_f32_16x16x32_bf16 v[78:81], v[166:169], v[198:201], v[78:81]
	v_mfma_f32_16x16x32_bf16 v[74:77], v[174:177], v[198:201], v[74:77]
	v_mfma_f32_16x16x32_bf16 v[70:73], v[166:169], v[206:209], v[70:73]
	v_mfma_f32_16x16x32_bf16 v[66:69], v[174:177], v[206:209], v[66:69]
	s_barrier
	s_add_i32 s34, s62, s48
	v_lshl_add_u64 v[210:211], s[44:45], 0, v[134:135]
	s_mov_b32 m0, s34
	ds_read_b128 v[178:181], v144 offset:16384
	ds_read_b128 v[182:185], v144 offset:17408
	ds_read_b128 v[186:189], v144 offset:18432
	ds_read_b128 v[190:193], v144 offset:19456
	ds_read_b128 v[194:197], v144 offset:20480
	ds_read_b128 v[198:201], v144 offset:21504
	ds_read_b128 v[202:205], v144 offset:22528
	ds_read_b128 v[206:209], v144 offset:23552
	global_load_lds_dwordx4 v[210:211], off
	s_add_i32 m0, s34, 0x2000
	s_add_u32 s34, s44, 0x20000
	v_lshl_add_u64 v[212:213], s[44:45], 0, v[130:131]
	s_addc_u32 s35, s45, 0
	s_add_i32 s62, s63, s48
	global_load_lds_dwordx4 v[212:213], off
	v_lshl_add_u64 v[214:215], s[34:35], 0, v[134:135]
	s_mov_b32 m0, s62
	v_lshl_add_u64 v[216:217], s[46:47], 0, v[132:133]
	global_load_lds_dwordx4 v[214:215], off
	v_lshl_add_u64 v[214:215], s[34:35], 0, v[130:131]
	s_add_i32 m0, s62, 0x2000
	s_nop 0
	global_load_lds_dwordx4 v[214:215], off
	v_lshl_add_u64 v[214:215], s[46:47], 0, v[136:137]
	s_mov_b32 m0, s7
	s_nop 0
	global_load_lds_dwordx4 v[214:215], off
	s_mov_b32 m0, s21
	s_nop 0
	global_load_lds_dwordx4 v[216:217], off
	s_waitcnt vmcnt(8)
	s_waitcnt lgkmcnt(0)
	s_barrier
; #define PG8_STAGE(bufoff, gbase, voff) do { _Pragma("unroll") for (int _i = 0; _i < 2; ++_i) \
;         __builtin_amdgcn_global_load_lds((const unsigned*)((const char*)(gbase) + (voff)[_i]), (PG8_LAS unsigned*)(lds + (bufoff) + ldsw + _i * 8192), 16, 0, 0); } while (0)
; #define PG8_LDA(dst, b, h) do { _Pragma("unroll") for (int m = 0; m < 4; ++m) _Pragma("unroll") for (int k = 0; k < 2; ++k) dst[m][k] = *(const PG8_LAS bf16x8*)(lds + PG8_SA(b, h) + aoff + m * 2048 + k * 1024); } while (0)
; #define PG8_LDB(dst, b, h) do { _Pragma("unroll") for (int n = 0; n < 2; ++n) _Pragma("unroll") for (int k = 0; k < 2; ++k) dst[n][k] = *(const PG8_LAS bf16x8*)(lds + PG8_SB(b, h) + boff + n * 2048 + k * 1024); } while (0)
; #define PG8_MMA(ai, bj, At, Bt) do { __builtin_amdgcn_s_setprio(1); _Pragma("unroll") for (int m = 0; m < 4; ++m) _Pragma("unroll") for (int n = 0; n < 2; ++n) _Pragma("unroll") for (int k = 0; k < 2; ++k) \
;         acc[ai][bj][m][n] = __builtin_amdgcn_mfma_f32_16x16x32_bf16(Bt[n][k], At[m][k], acc[ai][bj][m][n], 0, 0, 0); __builtin_amdgcn_s_setprio(0); } while (0)
; #define PG8_WAIT_V(n) asm volatile("s_waitcnt vmcnt(" #n ")" ::: "memory")
; #define PG8_WAIT_L(n) asm volatile("s_waitcnt lgkmcnt(" #n ")" ::: "memory")
; #define PG8_BAR __builtin_amdgcn_s_barrier()
; #define PG8_SCHED __builtin_amdgcn_sched_barrier(0)
; template <class Epi, class Sched, bool ALIGN_EPI = false, bool SP2 = false>
; __device__ __forceinline__ void gemm_phase(PG8_LAS unsigned char* lds, const Gemm g, const Sched& S, const Epi& E) {
;     ...
;             PG8_WAIT_V(8); PG8_WAIT_L(0); PG8_BAR; PG8_MMA(1, 0, At, B0); PG8_MMA(1, 1, At, B1); PG8_BAR; PG8_SCHED;
;             PG8_LDB(B0, 1, 0); PG8_LDB(B1, 1, 1); PG8_SCHED; PG8_LDA(At, 1, 0); PG8_STAGE(PG8_SA(0, 1), a2 + hstepA, voffA);
;             PG8_WAIT_V(8); PG8_WAIT_L(0); PG8_BAR; PG8_MMA(0, 0, At, B0); PG8_MMA(0, 1, At, B1); PG8_BAR; PG8_SCHED;
	s_waitcnt lgkmcnt(0)
	v_mfma_f32_16x16x32_bf16 v[62:65], v[146:149], v[178:181], v[62:65]
	v_mfma_f32_16x16x32_bf16 v[58:61], v[154:157], v[178:181], v[58:61]
	v_mfma_f32_16x16x32_bf16 v[54:57], v[146:149], v[186:189], v[54:57]
	v_mfma_f32_16x16x32_bf16 v[50:53], v[154:157], v[186:189], v[50:53]
	v_mfma_f32_16x16x32_bf16 v[38:41], v[146:149], v[194:197], v[38:41]
	v_mfma_f32_16x16x32_bf16 v[34:37], v[154:157], v[194:197], v[34:37]
	v_mfma_f32_16x16x32_bf16 v[22:25], v[146:149], v[202:205], v[22:25]
	v_mfma_f32_16x16x32_bf16 v[18:21], v[154:157], v[202:205], v[18:21]
	v_mfma_f32_16x16x32_bf16 v[62:65], v[150:153], v[182:185], v[62:65]
	v_mfma_f32_16x16x32_bf16 v[58:61], v[158:161], v[182:185], v[58:61]
	v_mfma_f32_16x16x32_bf16 v[54:57], v[150:153], v[190:193], v[54:57]
	v_mfma_f32_16x16x32_bf16 v[50:53], v[158:161], v[190:193], v[50:53]
	v_mfma_f32_16x16x32_bf16 v[38:41], v[150:153], v[198:201], v[38:41]
	v_mfma_f32_16x16x32_bf16 v[34:37], v[158:161], v[198:201], v[34:37]
	v_mfma_f32_16x16x32_bf16 v[22:25], v[150:153], v[206:209], v[22:25]
	v_mfma_f32_16x16x32_bf16 v[18:21], v[158:161], v[206:209], v[18:21]
	v_mfma_f32_16x16x32_bf16 v[46:49], v[162:165], v[178:181], v[46:49]
	v_mfma_f32_16x16x32_bf16 v[42:45], v[170:173], v[178:181], v[42:45]
	v_mfma_f32_16x16x32_bf16 v[30:33], v[162:165], v[186:189], v[30:33]
	v_mfma_f32_16x16x32_bf16 v[26:29], v[170:173], v[186:189], v[26:29]
	v_mfma_f32_16x16x32_bf16 v[14:17], v[162:165], v[194:197], v[14:17]
	v_mfma_f32_16x16x32_bf16 v[10:13], v[170:173], v[194:197], v[10:13]
	v_mfma_f32_16x16x32_bf16 v[6:9], v[162:165], v[202:205], v[6:9]
	v_mfma_f32_16x16x32_bf16 v[2:5], v[170:173], v[202:205], v[2:5]
	v_mfma_f32_16x16x32_bf16 v[46:49], v[166:169], v[182:185], v[46:49]
	v_mfma_f32_16x16x32_bf16 v[42:45], v[174:177], v[182:185], v[42:45]
	v_mfma_f32_16x16x32_bf16 v[30:33], v[166:169], v[190:193], v[30:33]
	v_mfma_f32_16x16x32_bf16 v[26:29], v[174:177], v[190:193], v[26:29]
	v_mfma_f32_16x16x32_bf16 v[14:17], v[166:169], v[198:201], v[14:17]
	v_mfma_f32_16x16x32_bf16 v[10:13], v[174:177], v[198:201], v[10:13]
	v_mfma_f32_16x16x32_bf16 v[6:9], v[166:169], v[206:209], v[6:9]
	v_mfma_f32_16x16x32_bf16 v[2:5], v[174:177], v[206:209], v[2:5]
	s_barrier
	s_add_i32 s62, 0, 0x18000
	v_add_u32_e32 v145, s62, v142
	s_add_i32 s63, 0, 0x1c000
	ds_read_b128 v[146:149], v145
	ds_read_b128 v[150:153], v145 offset:1024
	ds_read_b128 v[154:157], v145 offset:2048
	ds_read_b128 v[158:161], v145 offset:3072
	v_add_u32_e32 v145, s63, v142
	ds_read_b128 v[162:165], v145
	ds_read_b128 v[166:169], v145 offset:1024
	ds_read_b128 v[170:173], v145 offset:2048
	ds_read_b128 v[174:177], v145 offset:3072
	s_add_u32 s34, s46, 0x40000
	s_addc_u32 s35, s47, 0
	s_mov_b32 m0, s51
	v_lshl_add_u64 v[218:219], s[34:35], 0, v[136:137]
	ds_read_b128 v[178:181], v144 offset:32768
	ds_read_b128 v[182:185], v144 offset:33792
	ds_read_b128 v[186:189], v144 offset:34816
	ds_read_b128 v[190:193], v144 offset:35840
	ds_read_b128 v[194:197], v144 offset:36864
	ds_read_b128 v[198:201], v144 offset:37888
	ds_read_b128 v[202:205], v144 offset:38912
	ds_read_b128 v[206:209], v144 offset:39936
	global_load_lds_dwordx4 v[218:219], off
	v_lshl_add_u64 v[218:219], s[34:35], 0, v[132:133]
	s_mov_b32 m0, s52
	s_nop 0
	global_load_lds_dwordx4 v[218:219], off
	s_waitcnt vmcnt(8)
	s_waitcnt lgkmcnt(0)
	s_barrier
	s_waitcnt lgkmcnt(0)
	v_mfma_f32_16x16x32_bf16 v[126:129], v[146:149], v[178:181], v[126:129]
	v_mfma_f32_16x16x32_bf16 v[122:125], v[154:157], v[178:181], v[122:125]
	v_mfma_f32_16x16x32_bf16 v[118:121], v[146:149], v[186:189], v[118:121]
	v_mfma_f32_16x16x32_bf16 v[114:117], v[154:157], v[186:189], v[114:117]
	v_mfma_f32_16x16x32_bf16 v[102:105], v[146:149], v[194:197], v[102:105]
	v_mfma_f32_16x16x32_bf16 v[98:101], v[154:157], v[194:197], v[98:101]
	v_mfma_f32_16x16x32_bf16 v[86:89], v[146:149], v[202:205], v[86:89]
	v_mfma_f32_16x16x32_bf16 v[82:85], v[154:157], v[202:205], v[82:85]
	v_mfma_f32_16x16x32_bf16 v[126:129], v[150:153], v[182:185], v[126:129]
	v_mfma_f32_16x16x32_bf16 v[122:125], v[158:161], v[182:185], v[122:125]
	v_mfma_f32_16x16x32_bf16 v[118:121], v[150:153], v[190:193], v[118:121]
	v_mfma_f32_16x16x32_bf16 v[114:117], v[158:161], v[190:193], v[114:117]
	v_mfma_f32_16x16x32_bf16 v[102:105], v[150:153], v[198:201], v[102:105]
	v_mfma_f32_16x16x32_bf16 v[98:101], v[158:161], v[198:201], v[98:101]
	v_mfma_f32_16x16x32_bf16 v[86:89], v[150:153], v[206:209], v[86:89]
	v_mfma_f32_16x16x32_bf16 v[82:85], v[158:161], v[206:209], v[82:85]
	v_mfma_f32_16x16x32_bf16 v[110:113], v[162:165], v[178:181], v[110:113]
	v_mfma_f32_16x16x32_bf16 v[106:109], v[170:173], v[178:181], v[106:109]
	v_mfma_f32_16x16x32_bf16 v[94:97], v[162:165], v[186:189], v[94:97]
	v_mfma_f32_16x16x32_bf16 v[90:93], v[170:173], v[186:189], v[90:93]
	v_mfma_f32_16x16x32_bf16 v[78:81], v[162:165], v[194:197], v[78:81]
	v_mfma_f32_16x16x32_bf16 v[74:77], v[170:173], v[194:197], v[74:77]
	v_mfma_f32_16x16x32_bf16 v[70:73], v[162:165], v[202:205], v[70:73]
	v_mfma_f32_16x16x32_bf16 v[66:69], v[170:173], v[202:205], v[66:69]
	v_mfma_f32_16x16x32_bf16 v[110:113], v[166:169], v[182:185], v[110:113]
	v_mfma_f32_16x16x32_bf16 v[106:109], v[174:177], v[182:185], v[106:109]
	v_mfma_f32_16x16x32_bf16 v[94:97], v[166:169], v[190:193], v[94:97]
	v_mfma_f32_16x16x32_bf16 v[90:93], v[174:177], v[190:193], v[90:93]
	v_mfma_f32_16x16x32_bf16 v[78:81], v[166:169], v[198:201], v[78:81]
	v_mfma_f32_16x16x32_bf16 v[74:77], v[174:177], v[198:201], v[74:77]
	v_mfma_f32_16x16x32_bf16 v[70:73], v[166:169], v[206:209], v[70:73]
	v_mfma_f32_16x16x32_bf16 v[66:69], v[174:177], v[206:209], v[66:69]
	s_barrier
; #define PG8_STAGE(bufoff, gbase, voff) do { _Pragma("unroll") for (int _i = 0; _i < 2; ++_i) \
;         __builtin_amdgcn_global_load_lds((const unsigned*)((const char*)(gbase) + (voff)[_i]), (PG8_LAS unsigned*)(lds + (bufoff) + ldsw + _i * 8192), 16, 0, 0); } while (0)
; #define PG8_LDA(dst, b, h) do { _Pragma("unroll") for (int m = 0; m < 4; ++m) _Pragma("unroll") for (int k = 0; k < 2; ++k) dst[m][k] = *(const PG8_LAS bf16x8*)(lds + PG8_SA(b, h) + aoff + m * 2048 + k * 1024); } while (0)
; #define PG8_MMA(ai, bj, At, Bt) do { __builtin_amdgcn_s_setprio(1); _Pragma("unroll") for (int m = 0; m < 4; ++m) _Pragma("unroll") for (int n = 0; n < 2; ++n) _Pragma("unroll") for (int k = 0; k < 2; ++k) \
;         acc[ai][bj][m][n] = __builtin_amdgcn_mfma_f32_16x16x32_bf16(Bt[n][k], At[m][k], acc[ai][bj][m][n], 0, 0, 0); __builtin_amdgcn_s_setprio(0); } while (0)
; #define PG8_WAIT_V(n) asm volatile("s_waitcnt vmcnt(" #n ")" ::: "memory")
; #define PG8_WAIT_L(n) asm volatile("s_waitcnt lgkmcnt(" #n ")" ::: "memory")
; #define PG8_BAR __builtin_amdgcn_s_barrier()
; #define PG8_SCHED __builtin_amdgcn_sched_barrier(0)
; template <class Epi, class Sched, bool ALIGN_EPI = false, bool SP2 = false>
; __device__ __forceinline__ void gemm_phase(PG8_LAS unsigned char* lds, const Gemm g, const Sched& S, const Epi& E) {
;     ...
;             PG8_LDA(At, 1, 1); PG8_STAGE(PG8_SB(1, 0), b3, voffB); PG8_STAGE(PG8_SB(1, 1), b3 + hstep, voffB); PG8_STAGE(PG8_SA(1, 0), a3, voffA);
;             PG8_WAIT_V(8); PG8_WAIT_L(0); PG8_BAR; PG8_MMA(1, 0, At, B0); PG8_MMA(1, 1, At, B1); PG8_BAR; PG8_SCHED;
	s_add_i32 s34, s62, s48
	v_lshl_add_u64 v[210:211], v[210:211], 0, s[12:13]
	s_mov_b32 m0, s34
	ds_read_b128 v[178:181], v144 offset:49152
	ds_read_b128 v[182:185], v144 offset:50176
	ds_read_b128 v[186:189], v144 offset:51200
	ds_read_b128 v[190:193], v144 offset:52224
	ds_read_b128 v[194:197], v144 offset:53248
	ds_read_b128 v[198:201], v144 offset:54272
	ds_read_b128 v[202:205], v144 offset:55296
	ds_read_b128 v[206:209], v144 offset:56320
	global_load_lds_dwordx4 v[210:211], off
	s_add_i32 m0, s34, 0x2000
	s_add_u32 s34, s44, 0x20080
	v_lshl_add_u64 v[210:211], v[212:213], 0, s[12:13]
	s_addc_u32 s35, s45, 0
	s_add_i32 s44, s63, s48
	global_load_lds_dwordx4 v[210:211], off
	v_lshl_add_u64 v[210:211], s[34:35], 0, v[134:135]
	s_mov_b32 m0, s44
	s_nop 0
	global_load_lds_dwordx4 v[210:211], off
	v_lshl_add_u64 v[210:211], s[34:35], 0, v[130:131]
	s_add_i32 m0, s44, 0x2000
	s_nop 0
	global_load_lds_dwordx4 v[210:211], off
	v_lshl_add_u64 v[210:211], v[214:215], 0, s[12:13]
	s_mov_b32 m0, s53
	s_nop 0
	global_load_lds_dwordx4 v[210:211], off
	v_lshl_add_u64 v[210:211], v[216:217], 0, s[12:13]
	s_mov_b32 m0, s54
	s_nop 0
	global_load_lds_dwordx4 v[210:211], off
	s_waitcnt vmcnt(8)
	s_waitcnt lgkmcnt(0)
	s_barrier
	s_waitcnt lgkmcnt(0)
	v_mfma_f32_16x16x32_bf16 v[62:65], v[146:149], v[178:181], v[62:65]
	v_mfma_f32_16x16x32_bf16 v[58:61], v[154:157], v[178:181], v[58:61]
	v_mfma_f32_16x16x32_bf16 v[54:57], v[146:149], v[186:189], v[54:57]
	v_mfma_f32_16x16x32_bf16 v[50:53], v[154:157], v[186:189], v[50:53]
	v_mfma_f32_16x16x32_bf16 v[38:41], v[146:149], v[194:197], v[38:41]
	v_mfma_f32_16x16x32_bf16 v[34:37], v[154:157], v[194:197], v[34:37]
	v_mfma_f32_16x16x32_bf16 v[22:25], v[146:149], v[202:205], v[22:25]
	v_mfma_f32_16x16x32_bf16 v[18:21], v[154:157], v[202:205], v[18:21]
	v_mfma_f32_16x16x32_bf16 v[62:65], v[150:153], v[182:185], v[62:65]
	v_mfma_f32_16x16x32_bf16 v[58:61], v[158:161], v[182:185], v[58:61]
	v_mfma_f32_16x16x32_bf16 v[54:57], v[150:153], v[190:193], v[54:57]
	v_mfma_f32_16x16x32_bf16 v[50:53], v[158:161], v[190:193], v[50:53]
	v_mfma_f32_16x16x32_bf16 v[38:41], v[150:153], v[198:201], v[38:41]
	v_mfma_f32_16x16x32_bf16 v[34:37], v[158:161], v[198:201], v[34:37]
	v_mfma_f32_16x16x32_bf16 v[22:25], v[150:153], v[206:209], v[22:25]
	v_mfma_f32_16x16x32_bf16 v[18:21], v[158:161], v[206:209], v[18:21]
	v_mfma_f32_16x16x32_bf16 v[46:49], v[162:165], v[178:181], v[46:49]
	v_mfma_f32_16x16x32_bf16 v[42:45], v[170:173], v[178:181], v[42:45]
	v_mfma_f32_16x16x32_bf16 v[30:33], v[162:165], v[186:189], v[30:33]
	v_mfma_f32_16x16x32_bf16 v[26:29], v[170:173], v[186:189], v[26:29]
	v_mfma_f32_16x16x32_bf16 v[14:17], v[162:165], v[194:197], v[14:17]
	v_mfma_f32_16x16x32_bf16 v[10:13], v[170:173], v[194:197], v[10:13]
	v_mfma_f32_16x16x32_bf16 v[6:9], v[162:165], v[202:205], v[6:9]
	v_mfma_f32_16x16x32_bf16 v[2:5], v[170:173], v[202:205], v[2:5]
	v_mfma_f32_16x16x32_bf16 v[46:49], v[166:169], v[182:185], v[46:49]
	v_mfma_f32_16x16x32_bf16 v[42:45], v[174:177], v[182:185], v[42:45]
	v_mfma_f32_16x16x32_bf16 v[30:33], v[166:169], v[190:193], v[30:33]
	v_mfma_f32_16x16x32_bf16 v[26:29], v[174:177], v[190:193], v[26:29]
	v_mfma_f32_16x16x32_bf16 v[14:17], v[166:169], v[198:201], v[14:17]
	v_mfma_f32_16x16x32_bf16 v[10:13], v[174:177], v[198:201], v[10:13]
	v_mfma_f32_16x16x32_bf16 v[6:9], v[166:169], v[206:209], v[6:9]
	v_mfma_f32_16x16x32_bf16 v[2:5], v[174:177], v[206:209], v[2:5]
	s_barrier
	s_add_i32 s61, s61, 2
	s_add_u32 s42, s42, 0x100
	s_addc_u32 s43, s43, 0
	s_add_u32 s59, s59, 0x100
	s_addc_u32 s60, s60, 0
	s_cmp_gt_u32 s61, 5
	s_cbranch_scc0 .LBB0_231
; __device__ __forceinline__ u32x4 pack8(const f32x4 a, const f32x4 b) { u32x4 w; w.x = cvt_pk_bf16(a[0], a[1]); w.y = cvt_pk_bf16(a[2], a[3]); w.z = cvt_pk_bf16(b[0], b[1]); w.w = cvt_pk_bf16(b[2], b[3]); return w; }
;     __device__ __forceinline__ void operator()(const f32x4 (&acc)[2][2][4][2], const Unit& u, int wr, int wc, int fr, int fq) const {
;         const int row0 = u.pm * BM + wr * 64 + fr, col0 = u.pn * BM + wc * 32 + 8 * fq;
; #pragma unroll
;         for (int ai = 0; ai < 2; ++ai)
; #pragma unroll
;             for (int m = 0; m < 4; ++m) {
;                 bf16_t* rowp = Y + (size_t)(row0 + ai * HALF + m * 16) * LDG_ + col0;
; #pragma unroll
;                 for (int bj = 0; bj < 2; ++bj) *(u32x4*)(rowp + bj * HALF) = pack8(acc[ai][bj][m][0], acc[ai][bj][m][1]);
;             }
;     }
	v_lshl_add_u32 v146, s20, 8, v1
	v_lshl_or_b32 v148, s6, 8, v143
	v_ashrrev_i32_e32 v147, 31, v146
	v_ashrrev_i32_e32 v149, 31, v148
	v_lshlrev_b64 v[150:151], 12, v[146:147]
	v_lshl_add_u64 v[150:151], s[16:17], 0, v[150:151]
	v_lshlrev_b64 v[148:149], 1, v[148:149]
	v_lshl_add_u64 v[150:151], v[150:151], 0, v[148:149]
	s_mov_b32 s6, 0x80000
	s_mov_b64 s[34:35], 0x80000
	v_cvt_pk_bf16_f32 v62, v62, v63
	v_cvt_pk_bf16_f32 v63, v64, v65
	v_cvt_pk_bf16_f32 v64, v58, v59
	v_add_co_u32_e32 v58, vcc, s6, v150
	v_cvt_pk_bf16_f32 v110, v110, v111
	v_cvt_pk_bf16_f32 v111, v112, v113
	v_cvt_pk_bf16_f32 v112, v106, v107
	v_or_b32_e32 v106, 16, v146
	v_cvt_pk_bf16_f32 v70, v70, v71
	v_cvt_pk_bf16_f32 v71, v72, v73
	v_cvt_pk_bf16_f32 v72, v66, v67
	v_lshl_add_u64 v[66:67], v[150:151], 0, s[34:35]
	v_addc_co_u32_e32 v59, vcc, 0, v151, vcc
	v_cvt_pk_bf16_f32 v46, v46, v47
	v_cvt_pk_bf16_f32 v47, v48, v49
	v_cvt_pk_bf16_f32 v48, v42, v43
	v_cvt_pk_bf16_f32 v49, v44, v45
	s_mov_b32 s6, 0x90000
	v_ashrrev_i32_e32 v107, 31, v106
	v_cvt_pk_bf16_f32 v94, v94, v95
	v_cvt_pk_bf16_f32 v95, v96, v97
	v_cvt_pk_bf16_f32 v96, v90, v91
	v_or_b32_e32 v90, 32, v146
	global_store_dwordx4 v[66:67], v[46:49], off offset:256
	s_mov_b64 s[34:35], 0x90000
	v_lshlrev_b64 v[106:107], 12, v[106:107]
	v_add_co_u32_e32 v48, vcc, s6, v150
	v_ashrrev_i32_e32 v91, 31, v90
	v_cvt_pk_bf16_f32 v78, v78, v79
	v_cvt_pk_bf16_f32 v79, v80, v81
	v_cvt_pk_bf16_f32 v80, v74, v75
	v_or_b32_e32 v74, 48, v146
	v_lshl_add_u64 v[46:47], v[150:151], 0, s[34:35]
	v_addc_co_u32_e32 v49, vcc, 0, v151, vcc
	v_cvt_pk_bf16_f32 v30, v30, v31
	v_cvt_pk_bf16_f32 v31, v32, v33
	v_cvt_pk_bf16_f32 v32, v26, v27
	v_cvt_pk_bf16_f32 v33, v28, v29
	s_mov_b32 s6, 0xa0000
	v_cvt_pk_bf16_f32 v113, v108, v109
	v_lshl_add_u64 v[106:107], s[16:17], 0, v[106:107]
	v_lshlrev_b64 v[90:91], 12, v[90:91]
	v_ashrrev_i32_e32 v75, 31, v74
	global_store_dwordx4 v[46:47], v[30:33], off offset:256
	s_mov_b64 s[34:35], 0xa0000
	global_store_dwordx4 v[150:151], v[110:113], off offset:256
	v_add_co_u32_e32 v32, vcc, s6, v150
	s_nop 0
	v_lshl_add_u64 v[110:111], v[106:107], 0, v[148:149]
	v_cvt_pk_bf16_f32 v97, v92, v93
	v_lshl_add_u64 v[90:91], s[16:17], 0, v[90:91]
	v_lshlrev_b64 v[74:75], 12, v[74:75]
	v_lshl_add_u64 v[30:31], v[150:151], 0, s[34:35]
	v_addc_co_u32_e32 v33, vcc, 0, v151, vcc
	v_cvt_pk_bf16_f32 v14, v14, v15
	v_cvt_pk_bf16_f32 v15, v16, v17
	v_cvt_pk_bf16_f32 v16, v10, v11
	v_cvt_pk_bf16_f32 v17, v12, v13
	s_mov_b32 s6, 0xb0000
	global_store_dwordx4 v[110:111], v[94:97], off offset:256
	v_cvt_pk_bf16_f32 v81, v76, v77
	v_lshl_add_u64 v[74:75], s[16:17], 0, v[74:75]
	v_lshl_add_u64 v[94:95], v[90:91], 0, v[148:149]
	global_store_dwordx4 v[30:31], v[14:17], off offset:256
	s_mov_b64 s[34:35], 0xb0000
	v_cvt_pk_bf16_f32 v126, v126, v127
	v_add_co_u32_e32 v16, vcc, s6, v150
	v_cvt_pk_bf16_f32 v127, v128, v129
	v_cvt_pk_bf16_f32 v128, v122, v123
	v_cvt_pk_bf16_f32 v129, v124, v125
	v_cvt_pk_bf16_f32 v106, v118, v119
	v_cvt_pk_bf16_f32 v107, v120, v121
	v_cvt_pk_bf16_f32 v108, v114, v115
	v_cvt_pk_bf16_f32 v109, v116, v117
	v_cvt_pk_bf16_f32 v90, v102, v103
	v_cvt_pk_bf16_f32 v91, v104, v105
	v_cvt_pk_bf16_f32 v92, v98, v99
	v_cvt_pk_bf16_f32 v93, v100, v101
	global_store_dwordx4 v[94:95], v[78:81], off offset:256
	v_cvt_pk_bf16_f32 v76, v82, v83
	v_cvt_pk_bf16_f32 v77, v84, v85
	v_lshl_add_u64 v[78:79], v[74:75], 0, v[148:149]
	v_cvt_pk_bf16_f32 v74, v86, v87
	v_cvt_pk_bf16_f32 v75, v88, v89
	v_cvt_pk_bf16_f32 v73, v68, v69
	v_cvt_pk_bf16_f32 v65, v60, v61
	v_cvt_pk_bf16_f32 v42, v54, v55
	v_cvt_pk_bf16_f32 v43, v56, v57
	v_cvt_pk_bf16_f32 v44, v50, v51
	v_cvt_pk_bf16_f32 v45, v52, v53
	v_cvt_pk_bf16_f32 v26, v38, v39
	v_cvt_pk_bf16_f32 v27, v40, v41
	v_cvt_pk_bf16_f32 v28, v34, v35
	v_cvt_pk_bf16_f32 v29, v36, v37
	v_lshl_add_u64 v[14:15], v[150:151], 0, s[34:35]
	v_cvt_pk_bf16_f32 v10, v22, v23
	v_cvt_pk_bf16_f32 v11, v24, v25
	v_cvt_pk_bf16_f32 v12, v18, v19
	v_cvt_pk_bf16_f32 v13, v20, v21
	v_addc_co_u32_e32 v17, vcc, 0, v151, vcc
	v_cvt_pk_bf16_f32 v6, v6, v7
	v_cvt_pk_bf16_f32 v7, v8, v9
	v_cvt_pk_bf16_f32 v8, v2, v3
	v_cvt_pk_bf16_f32 v9, v4, v5
	s_cmp_eq_u32 s56, s1
	s_mov_b32 s6, s26
	s_mov_b32 s20, s36
	s_mov_b64 s[44:45], s[40:41]
	s_mov_b64 s[42:43], s[38:39]
	s_mov_b32 s27, s56
	global_store_dwordx4 v[150:151], v[126:129], off
	global_store_dwordx4 v[110:111], v[106:109], off
	global_store_dwordx4 v[94:95], v[90:93], off
	global_store_dwordx4 v[78:79], v[74:77], off
	global_store_dwordx4 v[78:79], v[70:73], off offset:256
	global_store_dwordx4 v[58:59], v[62:65], off
	global_store_dwordx4 v[48:49], v[42:45], off
	global_store_dwordx4 v[32:33], v[26:29], off
	global_store_dwordx4 v[16:17], v[10:13], off
	global_store_dwordx4 v[14:15], v[6:9], off offset:256
	s_cbranch_scc0 .LBB0_228
	s_waitcnt vmcnt(0)
	s_cmpk_gt_u32 s22, 0xff
	s_cbranch_scc1 .LBB0_235
	s_barrier

; #define PG8_STAGE(bufoff, gbase, voff) do { _Pragma("unroll") for (int _i = 0; _i < 2; ++_i) \
;         __builtin_amdgcn_global_load_lds((const unsigned*)((const char*)(gbase) + (voff)[_i]), (PG8_LAS unsigned*)(lds + (bufoff) + ldsw + _i * 8192), 16, 0, 0); } while (0)
; #define PG8_LDA(dst, b, h) do { _Pragma("unroll") for (int m = 0; m < 4; ++m) _Pragma("unroll") for (int k = 0; k < 2; ++k) dst[m][k] = *(const PG8_LAS bf16x8*)(lds + PG8_SA(b, h) + aoff + m * 2048 + k * 1024); } while (0)
; #define PG8_LDB(dst, b, h) do { _Pragma("unroll") for (int n = 0; n < 2; ++n) _Pragma("unroll") for (int k = 0; k < 2; ++k) dst[n][k] = *(const PG8_LAS bf16x8*)(lds + PG8_SB(b, h) + boff + n * 2048 + k * 1024); } while (0)
; #define PG8_MMA(ai, bj, At, Bt) do { __builtin_amdgcn_s_setprio(1); _Pragma("unroll") for (int m = 0; m < 4; ++m) _Pragma("unroll") for (int n = 0; n < 2; ++n) _Pragma("unroll") for (int k = 0; k < 2; ++k) \
;         acc[ai][bj][m][n] = __builtin_amdgcn_mfma_f32_16x16x32_bf16(Bt[n][k], At[m][k], acc[ai][bj][m][n], 0, 0, 0); __builtin_amdgcn_s_setprio(0); } while (0)
; #define PG8_WAIT_V(n) asm volatile("s_waitcnt vmcnt(" #n ")" ::: "memory")
; #define PG8_WAIT_L(n) asm volatile("s_waitcnt lgkmcnt(" #n ")" ::: "memory")
; template <class Epi, class Sched, bool ALIGN_EPI = false, bool SP2 = false>
; __device__ __forceinline__ void gemm_phase(PG8_LAS unsigned char* lds, const Gemm g, const Sched& S, const Epi& E) {
;     ...
;             const bool last = (t == nt - 2);
;             const char* a1 = cA + (size_t)(t + 1) * kstep;
;             const char* a2 = last ? nA : cA + (size_t)(t + 2) * kstep; const char* b2 = last ? nB : cB + (size_t)(t + 2) * kstep;
;             const char* a3 = a2 + kstep; const char* b3 = b2 + kstep;
;             if (last && has_next) S.a_ready(nxt);
;             if constexpr (SP2) {
;             PG8_LDB(B0, 0, 0); PG8_LDB(B1, 0, 1); PG8_SCHED; PG8_LDA(At, 0, 0); PG8_STAGE(PG8_SA(1, 1), a1 + hstepA, voffA);
;             PG8_WAIT_V(8); PG8_WAIT_L(0); PG8_BAR; PG8_MMA(0, 0, At, B0); PG8_MMA(0, 1, At, B1); PG8_BAR; PG8_SCHED;
;             PG8_LDA(At, 0, 1); PG8_STAGE(PG8_SB(0, 0), b2, voffB); PG8_STAGE(PG8_SB(0, 1), b2 + hstep, voffB); PG8_STAGE(PG8_SA(0, 0), a2, voffA);
;             PG8_WAIT_V(8); PG8_WAIT_L(0); PG8_BAR; PG8_MMA(1, 0, At, B0); PG8_MMA(1, 1, At, B1); PG8_BAR; PG8_SCHED;
.LBB0_855:
	s_add_u32 s34, s48, 0xfffc0080
	s_addc_u32 s35, s49, -1
	s_add_i32 s69, 0, 0x10000
	s_cmp_eq_u32 s68, 12
	s_cselect_b32 s53, s39, s35
	s_cselect_b32 s52, s41, s34
	s_cselect_b32 s51, s27, s67
	s_cselect_b32 s50, s43, s66
	s_add_i32 s34, 0, 0x14000
	v_add_u32_e32 v46, s69, v191
	v_add_u32_e32 v174, s34, v191
	ds_read_b128 v[34:37], v46
	ds_read_b128 v[38:41], v46 offset:1024
	ds_read_b128 v[42:45], v46 offset:2048
	ds_read_b128 v[46:49], v46 offset:3072
	ds_read_b128 v[146:149], v174
	ds_read_b128 v[150:153], v174 offset:1024
	ds_read_b128 v[154:157], v174 offset:2048
	ds_read_b128 v[174:177], v174 offset:3072
	v_lshl_add_u64 v[214:215], s[48:49], 0, v[170:171]
	s_add_i32 m0, s56, 0xc000
	ds_read_b128 v[178:181], v193
	ds_read_b128 v[182:185], v193 offset:1024
	ds_read_b128 v[186:189], v193 offset:2048
	ds_read_b128 v[194:197], v193 offset:3072
	ds_read_b128 v[198:201], v193 offset:4096
	ds_read_b128 v[202:205], v193 offset:5120
	ds_read_b128 v[206:209], v193 offset:6144
	ds_read_b128 v[210:213], v193 offset:7168
	global_load_lds_dwordx4 v[214:215], off
	v_lshl_add_u64 v[214:215], s[48:49], 0, v[172:173]
	s_add_i32 m0, s56, 0xe000
	s_nop 0
	global_load_lds_dwordx4 v[214:215], off
	s_waitcnt vmcnt(8)
	s_waitcnt lgkmcnt(0)
	s_barrier
	s_waitcnt lgkmcnt(0)
	v_mfma_f32_16x16x32_bf16 v[142:145], v[34:37], v[178:181], v[142:145]
	v_mfma_f32_16x16x32_bf16 v[138:141], v[42:45], v[178:181], v[138:141]
	v_mfma_f32_16x16x32_bf16 v[126:129], v[34:37], v[186:189], v[126:129]
	v_mfma_f32_16x16x32_bf16 v[122:125], v[42:45], v[186:189], v[122:125]
	v_mfma_f32_16x16x32_bf16 v[110:113], v[34:37], v[198:201], v[110:113]
	v_mfma_f32_16x16x32_bf16 v[106:109], v[42:45], v[198:201], v[106:109]
	v_mfma_f32_16x16x32_bf16 v[94:97], v[34:37], v[206:209], v[94:97]
	v_mfma_f32_16x16x32_bf16 v[90:93], v[42:45], v[206:209], v[90:93]
	v_mfma_f32_16x16x32_bf16 v[142:145], v[38:41], v[182:185], v[142:145]
	v_mfma_f32_16x16x32_bf16 v[138:141], v[46:49], v[182:185], v[138:141]
	v_mfma_f32_16x16x32_bf16 v[126:129], v[38:41], v[194:197], v[126:129]
	v_mfma_f32_16x16x32_bf16 v[122:125], v[46:49], v[194:197], v[122:125]
	v_mfma_f32_16x16x32_bf16 v[110:113], v[38:41], v[202:205], v[110:113]
	v_mfma_f32_16x16x32_bf16 v[106:109], v[46:49], v[202:205], v[106:109]
	v_mfma_f32_16x16x32_bf16 v[94:97], v[38:41], v[210:213], v[94:97]
	v_mfma_f32_16x16x32_bf16 v[90:93], v[46:49], v[210:213], v[90:93]
	v_mfma_f32_16x16x32_bf16 v[134:137], v[146:149], v[178:181], v[134:137]
	v_mfma_f32_16x16x32_bf16 v[130:133], v[154:157], v[178:181], v[130:133]
	v_mfma_f32_16x16x32_bf16 v[118:121], v[146:149], v[186:189], v[118:121]
	v_mfma_f32_16x16x32_bf16 v[114:117], v[154:157], v[186:189], v[114:117]
	v_mfma_f32_16x16x32_bf16 v[102:105], v[146:149], v[198:201], v[102:105]
	v_mfma_f32_16x16x32_bf16 v[98:101], v[154:157], v[198:201], v[98:101]
	v_mfma_f32_16x16x32_bf16 v[86:89], v[146:149], v[206:209], v[86:89]
	v_mfma_f32_16x16x32_bf16 v[82:85], v[154:157], v[206:209], v[82:85]
	v_mfma_f32_16x16x32_bf16 v[134:137], v[150:153], v[182:185], v[134:137]
	v_mfma_f32_16x16x32_bf16 v[130:133], v[174:177], v[182:185], v[130:133]
	v_mfma_f32_16x16x32_bf16 v[118:121], v[150:153], v[194:197], v[118:121]
	v_mfma_f32_16x16x32_bf16 v[114:117], v[174:177], v[194:197], v[114:117]
	v_mfma_f32_16x16x32_bf16 v[102:105], v[150:153], v[202:205], v[102:105]
	v_mfma_f32_16x16x32_bf16 v[98:101], v[174:177], v[202:205], v[98:101]
	v_mfma_f32_16x16x32_bf16 v[86:89], v[150:153], v[210:213], v[86:89]
	v_mfma_f32_16x16x32_bf16 v[82:85], v[174:177], v[210:213], v[82:85]
	s_barrier
	s_add_i32 s35, s69, s22
	v_lshl_add_u64 v[214:215], s[50:51], 0, v[160:161]
	s_mov_b32 m0, s35
	ds_read_b128 v[178:181], v193 offset:16384
	ds_read_b128 v[182:185], v193 offset:17408
	ds_read_b128 v[186:189], v193 offset:18432
	ds_read_b128 v[194:197], v193 offset:19456
	ds_read_b128 v[198:201], v193 offset:20480
	ds_read_b128 v[202:205], v193 offset:21504
	ds_read_b128 v[206:209], v193 offset:22528
	ds_read_b128 v[210:213], v193 offset:23552
	global_load_lds_dwordx4 v[214:215], off
	s_add_i32 m0, s35, 0x2000
	s_add_u32 s70, s50, 0x40000
	v_lshl_add_u64 v[216:217], s[50:51], 0, v[164:165]
	s_addc_u32 s71, s51, 0
	s_add_i32 s34, s34, s22
	global_load_lds_dwordx4 v[216:217], off
	v_lshl_add_u64 v[218:219], s[70:71], 0, v[160:161]
	s_mov_b32 m0, s34
	v_lshl_add_u64 v[220:221], s[52:53], 0, v[162:163]
	global_load_lds_dwordx4 v[218:219], off
	v_lshl_add_u64 v[218:219], s[70:71], 0, v[164:165]
	s_add_i32 m0, s34, 0x2000
	s_nop 0
	global_load_lds_dwordx4 v[218:219], off
	v_lshl_add_u64 v[218:219], s[52:53], 0, v[158:159]
	s_mov_b32 m0, s56
	s_nop 0
	global_load_lds_dwordx4 v[218:219], off
	s_mov_b32 m0, s57
	s_nop 0
	global_load_lds_dwordx4 v[220:221], off
	s_waitcnt vmcnt(8)
	s_waitcnt lgkmcnt(0)
	s_barrier
; #define PG8_STAGE(bufoff, gbase, voff) do { _Pragma("unroll") for (int _i = 0; _i < 2; ++_i) \
;         __builtin_amdgcn_global_load_lds((const unsigned*)((const char*)(gbase) + (voff)[_i]), (PG8_LAS unsigned*)(lds + (bufoff) + ldsw + _i * 8192), 16, 0, 0); } while (0)
; #define PG8_LDA(dst, b, h) do { _Pragma("unroll") for (int m = 0; m < 4; ++m) _Pragma("unroll") for (int k = 0; k < 2; ++k) dst[m][k] = *(const PG8_LAS bf16x8*)(lds + PG8_SA(b, h) + aoff + m * 2048 + k * 1024); } while (0)
; #define PG8_LDB(dst, b, h) do { _Pragma("unroll") for (int n = 0; n < 2; ++n) _Pragma("unroll") for (int k = 0; k < 2; ++k) dst[n][k] = *(const PG8_LAS bf16x8*)(lds + PG8_SB(b, h) + boff + n * 2048 + k * 1024); } while (0)
; #define PG8_MMA(ai, bj, At, Bt) do { __builtin_amdgcn_s_setprio(1); _Pragma("unroll") for (int m = 0; m < 4; ++m) _Pragma("unroll") for (int n = 0; n < 2; ++n) _Pragma("unroll") for (int k = 0; k < 2; ++k) \
;         acc[ai][bj][m][n] = __builtin_amdgcn_mfma_f32_16x16x32_bf16(Bt[n][k], At[m][k], acc[ai][bj][m][n], 0, 0, 0); __builtin_amdgcn_s_setprio(0); } while (0)
; #define PG8_WAIT_V(n) asm volatile("s_waitcnt vmcnt(" #n ")" ::: "memory")
; #define PG8_WAIT_L(n) asm volatile("s_waitcnt lgkmcnt(" #n ")" ::: "memory")
; #define PG8_BAR __builtin_amdgcn_s_barrier()
; #define PG8_SCHED __builtin_amdgcn_sched_barrier(0)
; template <class Epi, class Sched, bool ALIGN_EPI = false, bool SP2 = false>
; __device__ __forceinline__ void gemm_phase(PG8_LAS unsigned char* lds, const Gemm g, const Sched& S, const Epi& E) {
;     ...
;             PG8_WAIT_V(8); PG8_WAIT_L(0); PG8_BAR; PG8_MMA(1, 0, At, B0); PG8_MMA(1, 1, At, B1); PG8_BAR; PG8_SCHED;
;             PG8_LDB(B0, 1, 0); PG8_LDB(B1, 1, 1); PG8_SCHED; PG8_LDA(At, 1, 0); PG8_STAGE(PG8_SA(0, 1), a2 + hstepA, voffA);
;             PG8_WAIT_V(8); PG8_WAIT_L(0); PG8_BAR; PG8_MMA(0, 0, At, B0); PG8_MMA(0, 1, At, B1); PG8_BAR; PG8_SCHED;
	s_waitcnt lgkmcnt(0)
	v_mfma_f32_16x16x32_bf16 v[78:81], v[34:37], v[178:181], v[78:81]
	v_mfma_f32_16x16x32_bf16 v[74:77], v[42:45], v[178:181], v[74:77]
	v_mfma_f32_16x16x32_bf16 v[62:65], v[34:37], v[186:189], v[62:65]
	v_mfma_f32_16x16x32_bf16 v[58:61], v[42:45], v[186:189], v[58:61]
	v_mfma_f32_16x16x32_bf16 v[30:33], v[34:37], v[198:201], v[30:33]
	v_mfma_f32_16x16x32_bf16 v[26:29], v[42:45], v[198:201], v[26:29]
	v_mfma_f32_16x16x32_bf16 v[14:17], v[34:37], v[206:209], v[14:17]
	v_mfma_f32_16x16x32_bf16 v[10:13], v[42:45], v[206:209], v[10:13]
	v_mfma_f32_16x16x32_bf16 v[78:81], v[38:41], v[182:185], v[78:81]
	v_mfma_f32_16x16x32_bf16 v[74:77], v[46:49], v[182:185], v[74:77]
	v_mfma_f32_16x16x32_bf16 v[62:65], v[38:41], v[194:197], v[62:65]
	v_mfma_f32_16x16x32_bf16 v[58:61], v[46:49], v[194:197], v[58:61]
	v_mfma_f32_16x16x32_bf16 v[30:33], v[38:41], v[202:205], v[30:33]
	v_mfma_f32_16x16x32_bf16 v[26:29], v[46:49], v[202:205], v[26:29]
	v_mfma_f32_16x16x32_bf16 v[14:17], v[38:41], v[210:213], v[14:17]
	v_mfma_f32_16x16x32_bf16 v[10:13], v[46:49], v[210:213], v[10:13]
	v_mfma_f32_16x16x32_bf16 v[22:25], v[146:149], v[198:201], v[22:25]
	v_mfma_f32_16x16x32_bf16 v[18:21], v[154:157], v[198:201], v[18:21]
	v_mfma_f32_16x16x32_bf16 v[6:9], v[146:149], v[206:209], v[6:9]
	v_mfma_f32_16x16x32_bf16 v[2:5], v[154:157], v[206:209], v[2:5]
	v_mfma_f32_16x16x32_bf16 v[34:37], v[146:149], v[178:181], v[70:73]
	v_mfma_f32_16x16x32_bf16 v[38:41], v[154:157], v[178:181], v[66:69]
	v_mfma_f32_16x16x32_bf16 v[42:45], v[146:149], v[186:189], v[54:57]
	v_mfma_f32_16x16x32_bf16 v[46:49], v[154:157], v[186:189], v[50:53]
	v_mfma_f32_16x16x32_bf16 v[22:25], v[150:153], v[202:205], v[22:25]
	v_mfma_f32_16x16x32_bf16 v[18:21], v[174:177], v[202:205], v[18:21]
	v_mfma_f32_16x16x32_bf16 v[6:9], v[150:153], v[210:213], v[6:9]
	v_mfma_f32_16x16x32_bf16 v[2:5], v[174:177], v[210:213], v[2:5]
	v_mfma_f32_16x16x32_bf16 v[34:37], v[150:153], v[182:185], v[34:37]
	v_mfma_f32_16x16x32_bf16 v[38:41], v[174:177], v[182:185], v[38:41]
	v_mfma_f32_16x16x32_bf16 v[42:45], v[150:153], v[194:197], v[42:45]
	v_mfma_f32_16x16x32_bf16 v[46:49], v[174:177], v[194:197], v[46:49]
	s_barrier
	s_add_i32 s34, 0, 0x18000
	s_add_i32 s35, 0, 0x1c000
	v_add_u32_e32 v70, s34, v191
	v_add_u32_e32 v174, s35, v191
	ds_read_b128 v[50:53], v70
	ds_read_b128 v[54:57], v70 offset:1024
	ds_read_b128 v[66:69], v70 offset:2048
	ds_read_b128 v[70:73], v70 offset:3072
	ds_read_b128 v[146:149], v174
	ds_read_b128 v[150:153], v174 offset:1024
	ds_read_b128 v[154:157], v174 offset:2048
	ds_read_b128 v[174:177], v174 offset:3072
	s_add_u32 s52, s52, 0x40000
	s_addc_u32 s53, s53, 0
	s_mov_b32 m0, s58
	v_lshl_add_u64 v[222:223], s[52:53], 0, v[158:159]
	ds_read_b128 v[178:181], v193 offset:32768
	ds_read_b128 v[182:185], v193 offset:33792
	ds_read_b128 v[186:189], v193 offset:34816
	ds_read_b128 v[194:197], v193 offset:35840
	ds_read_b128 v[198:201], v193 offset:36864
	ds_read_b128 v[202:205], v193 offset:37888
	ds_read_b128 v[206:209], v193 offset:38912
	ds_read_b128 v[210:213], v193 offset:39936
	global_load_lds_dwordx4 v[222:223], off
	v_lshl_add_u64 v[222:223], s[52:53], 0, v[162:163]
	s_mov_b32 m0, s59
	s_nop 0
	global_load_lds_dwordx4 v[222:223], off
	s_waitcnt vmcnt(8)
	s_waitcnt lgkmcnt(0)
	s_barrier
	s_waitcnt lgkmcnt(0)
	v_mfma_f32_16x16x32_bf16 v[142:145], v[50:53], v[178:181], v[142:145]
	v_mfma_f32_16x16x32_bf16 v[138:141], v[66:69], v[178:181], v[138:141]
	v_mfma_f32_16x16x32_bf16 v[126:129], v[50:53], v[186:189], v[126:129]
	v_mfma_f32_16x16x32_bf16 v[122:125], v[66:69], v[186:189], v[122:125]
	v_mfma_f32_16x16x32_bf16 v[110:113], v[50:53], v[198:201], v[110:113]
	v_mfma_f32_16x16x32_bf16 v[106:109], v[66:69], v[198:201], v[106:109]
	v_mfma_f32_16x16x32_bf16 v[94:97], v[50:53], v[206:209], v[94:97]
	v_mfma_f32_16x16x32_bf16 v[90:93], v[66:69], v[206:209], v[90:93]
	v_mfma_f32_16x16x32_bf16 v[142:145], v[54:57], v[182:185], v[142:145]
	v_mfma_f32_16x16x32_bf16 v[138:141], v[70:73], v[182:185], v[138:141]
	v_mfma_f32_16x16x32_bf16 v[126:129], v[54:57], v[194:197], v[126:129]
	v_mfma_f32_16x16x32_bf16 v[122:125], v[70:73], v[194:197], v[122:125]
	v_mfma_f32_16x16x32_bf16 v[110:113], v[54:57], v[202:205], v[110:113]
	v_mfma_f32_16x16x32_bf16 v[106:109], v[70:73], v[202:205], v[106:109]
	v_mfma_f32_16x16x32_bf16 v[94:97], v[54:57], v[210:213], v[94:97]
	v_mfma_f32_16x16x32_bf16 v[90:93], v[70:73], v[210:213], v[90:93]
	v_mfma_f32_16x16x32_bf16 v[134:137], v[146:149], v[178:181], v[134:137]
	v_mfma_f32_16x16x32_bf16 v[130:133], v[154:157], v[178:181], v[130:133]
	v_mfma_f32_16x16x32_bf16 v[118:121], v[146:149], v[186:189], v[118:121]
	v_mfma_f32_16x16x32_bf16 v[114:117], v[154:157], v[186:189], v[114:117]
	v_mfma_f32_16x16x32_bf16 v[102:105], v[146:149], v[198:201], v[102:105]
	v_mfma_f32_16x16x32_bf16 v[98:101], v[154:157], v[198:201], v[98:101]
	v_mfma_f32_16x16x32_bf16 v[86:89], v[146:149], v[206:209], v[86:89]
	v_mfma_f32_16x16x32_bf16 v[82:85], v[154:157], v[206:209], v[82:85]
	v_mfma_f32_16x16x32_bf16 v[134:137], v[150:153], v[182:185], v[134:137]
	v_mfma_f32_16x16x32_bf16 v[130:133], v[174:177], v[182:185], v[130:133]
	v_mfma_f32_16x16x32_bf16 v[118:121], v[150:153], v[194:197], v[118:121]
	v_mfma_f32_16x16x32_bf16 v[114:117], v[174:177], v[194:197], v[114:117]
	v_mfma_f32_16x16x32_bf16 v[102:105], v[150:153], v[202:205], v[102:105]
	v_mfma_f32_16x16x32_bf16 v[98:101], v[174:177], v[202:205], v[98:101]
	v_mfma_f32_16x16x32_bf16 v[86:89], v[150:153], v[210:213], v[86:89]
	v_mfma_f32_16x16x32_bf16 v[82:85], v[174:177], v[210:213], v[82:85]
	s_barrier
; #define PG8_STAGE(bufoff, gbase, voff) do { _Pragma("unroll") for (int _i = 0; _i < 2; ++_i) \
;         __builtin_amdgcn_global_load_lds((const unsigned*)((const char*)(gbase) + (voff)[_i]), (PG8_LAS unsigned*)(lds + (bufoff) + ldsw + _i * 8192), 16, 0, 0); } while (0)
; #define PG8_LDA(dst, b, h) do { _Pragma("unroll") for (int m = 0; m < 4; ++m) _Pragma("unroll") for (int k = 0; k < 2; ++k) dst[m][k] = *(const PG8_LAS bf16x8*)(lds + PG8_SA(b, h) + aoff + m * 2048 + k * 1024); } while (0)
; #define PG8_MMA(ai, bj, At, Bt) do { __builtin_amdgcn_s_setprio(1); _Pragma("unroll") for (int m = 0; m < 4; ++m) _Pragma("unroll") for (int n = 0; n < 2; ++n) _Pragma("unroll") for (int k = 0; k < 2; ++k) \
;         acc[ai][bj][m][n] = __builtin_amdgcn_mfma_f32_16x16x32_bf16(Bt[n][k], At[m][k], acc[ai][bj][m][n], 0, 0, 0); __builtin_amdgcn_s_setprio(0); } while (0)
; #define PG8_WAIT_V(n) asm volatile("s_waitcnt vmcnt(" #n ")" ::: "memory")
; #define PG8_WAIT_L(n) asm volatile("s_waitcnt lgkmcnt(" #n ")" ::: "memory")
; #define PG8_BAR __builtin_amdgcn_s_barrier()
; #define PG8_SCHED __builtin_amdgcn_sched_barrier(0)
; template <class Epi, class Sched, bool ALIGN_EPI = false, bool SP2 = false>
; __device__ __forceinline__ void gemm_phase(PG8_LAS unsigned char* lds, const Gemm g, const Sched& S, const Epi& E) {
;     ...
;             PG8_LDA(At, 1, 1); PG8_STAGE(PG8_SB(1, 0), b3, voffB); PG8_STAGE(PG8_SB(1, 1), b3 + hstep, voffB); PG8_STAGE(PG8_SA(1, 0), a3, voffA);
;             PG8_WAIT_V(8); PG8_WAIT_L(0); PG8_BAR; PG8_MMA(1, 0, At, B0); PG8_MMA(1, 1, At, B1); PG8_BAR; PG8_SCHED;
;     ...
;         if constexpr (ALIGN_EPI) { if (wr == 0) PG8_BAR; }
	s_add_i32 s34, s34, s22
	v_lshl_add_u64 v[214:215], v[214:215], 0, s[12:13]
	s_mov_b32 m0, s34
	ds_read_b128 v[178:181], v193 offset:49152
	ds_read_b128 v[182:185], v193 offset:50176
	ds_read_b128 v[186:189], v193 offset:51200
	ds_read_b128 v[194:197], v193 offset:52224
	ds_read_b128 v[198:201], v193 offset:53248
	ds_read_b128 v[202:205], v193 offset:54272
	ds_read_b128 v[206:209], v193 offset:55296
	ds_read_b128 v[210:213], v193 offset:56320
	global_load_lds_dwordx4 v[214:215], off
	s_add_i32 m0, s34, 0x2000
	s_add_u32 s50, s50, 0x40080
	v_lshl_add_u64 v[214:215], v[216:217], 0, s[12:13]
	s_addc_u32 s51, s51, 0
	s_add_i32 s34, s35, s22
	global_load_lds_dwordx4 v[214:215], off
	v_lshl_add_u64 v[214:215], s[50:51], 0, v[160:161]
	s_mov_b32 m0, s34
	s_nop 0
	global_load_lds_dwordx4 v[214:215], off
	v_lshl_add_u64 v[214:215], s[50:51], 0, v[164:165]
	s_add_i32 m0, s34, 0x2000
	s_nop 0
	global_load_lds_dwordx4 v[214:215], off
	v_lshl_add_u64 v[214:215], v[218:219], 0, s[12:13]
	s_mov_b32 m0, s60
	s_nop 0
	global_load_lds_dwordx4 v[214:215], off
	v_lshl_add_u64 v[214:215], v[220:221], 0, s[12:13]
	s_mov_b32 m0, s61
	s_nop 0
	global_load_lds_dwordx4 v[214:215], off
	s_waitcnt vmcnt(8)
	s_waitcnt lgkmcnt(0)
	s_barrier
	s_waitcnt lgkmcnt(0)
	v_mfma_f32_16x16x32_bf16 v[78:81], v[50:53], v[178:181], v[78:81]
	v_mfma_f32_16x16x32_bf16 v[74:77], v[66:69], v[178:181], v[74:77]
	v_mfma_f32_16x16x32_bf16 v[62:65], v[50:53], v[186:189], v[62:65]
	v_mfma_f32_16x16x32_bf16 v[58:61], v[66:69], v[186:189], v[58:61]
	v_mfma_f32_16x16x32_bf16 v[30:33], v[50:53], v[198:201], v[30:33]
	v_mfma_f32_16x16x32_bf16 v[26:29], v[66:69], v[198:201], v[26:29]
	v_mfma_f32_16x16x32_bf16 v[14:17], v[50:53], v[206:209], v[14:17]
	v_mfma_f32_16x16x32_bf16 v[10:13], v[66:69], v[206:209], v[10:13]
	v_mfma_f32_16x16x32_bf16 v[78:81], v[54:57], v[182:185], v[78:81]
	v_mfma_f32_16x16x32_bf16 v[74:77], v[70:73], v[182:185], v[74:77]
	v_mfma_f32_16x16x32_bf16 v[62:65], v[54:57], v[194:197], v[62:65]
	v_mfma_f32_16x16x32_bf16 v[58:61], v[70:73], v[194:197], v[58:61]
	v_mfma_f32_16x16x32_bf16 v[30:33], v[54:57], v[202:205], v[30:33]
	v_mfma_f32_16x16x32_bf16 v[26:29], v[70:73], v[202:205], v[26:29]
	v_mfma_f32_16x16x32_bf16 v[14:17], v[54:57], v[210:213], v[14:17]
	v_mfma_f32_16x16x32_bf16 v[10:13], v[70:73], v[210:213], v[10:13]
	v_mfma_f32_16x16x32_bf16 v[34:37], v[146:149], v[178:181], v[34:37]
	v_mfma_f32_16x16x32_bf16 v[70:73], v[150:153], v[182:185], v[34:37]
	v_mfma_f32_16x16x32_bf16 v[34:37], v[154:157], v[178:181], v[38:41]
	v_mfma_f32_16x16x32_bf16 v[66:69], v[174:177], v[182:185], v[34:37]
	v_mfma_f32_16x16x32_bf16 v[34:37], v[146:149], v[186:189], v[42:45]
	v_mfma_f32_16x16x32_bf16 v[54:57], v[150:153], v[194:197], v[34:37]
	v_mfma_f32_16x16x32_bf16 v[34:37], v[154:157], v[186:189], v[46:49]
	v_mfma_f32_16x16x32_bf16 v[22:25], v[146:149], v[198:201], v[22:25]
	v_mfma_f32_16x16x32_bf16 v[18:21], v[154:157], v[198:201], v[18:21]
	v_mfma_f32_16x16x32_bf16 v[6:9], v[146:149], v[206:209], v[6:9]
	v_mfma_f32_16x16x32_bf16 v[2:5], v[154:157], v[206:209], v[2:5]
	v_mfma_f32_16x16x32_bf16 v[50:53], v[174:177], v[194:197], v[34:37]
	v_mfma_f32_16x16x32_bf16 v[22:25], v[150:153], v[202:205], v[22:25]
	v_mfma_f32_16x16x32_bf16 v[18:21], v[174:177], v[202:205], v[18:21]
	v_mfma_f32_16x16x32_bf16 v[6:9], v[150:153], v[210:213], v[6:9]
	v_mfma_f32_16x16x32_bf16 v[2:5], v[174:177], v[210:213], v[2:5]
	s_barrier
	s_add_i32 s68, s68, 2
	s_add_u32 s48, s48, 0x100
	s_addc_u32 s49, s49, 0
	s_add_u32 s66, s66, 0x100
	s_addc_u32 s67, s67, 0
	s_cmp_gt_u32 s68, 13
	s_cbranch_scc0 .LBB0_855
	s_and_b64 vcc, exec, s[6:7]
	s_cbranch_vccz .LBB0_858
	s_barrier

; #define PG8_STAGE(bufoff, gbase, voff) do { _Pragma("unroll") for (int _i = 0; _i < 2; ++_i) \
;         __builtin_amdgcn_global_load_lds((const unsigned*)((const char*)(gbase) + (voff)[_i]), (PG8_LAS unsigned*)(lds + (bufoff) + ldsw + _i * 8192), 16, 0, 0); } while (0)
; #define PG8_LDA(dst, b, h) do { _Pragma("unroll") for (int m = 0; m < 4; ++m) _Pragma("unroll") for (int k = 0; k < 2; ++k) dst[m][k] = *(const PG8_LAS bf16x8*)(lds + PG8_SA(b, h) + aoff + m * 2048 + k * 1024); } while (0)
; #define PG8_LDB(dst, b, h) do { _Pragma("unroll") for (int n = 0; n < 2; ++n) _Pragma("unroll") for (int k = 0; k < 2; ++k) dst[n][k] = *(const PG8_LAS bf16x8*)(lds + PG8_SB(b, h) + boff + n * 2048 + k * 1024); } while (0)
; #define PG8_MMA(ai, bj, At, Bt) do { __builtin_amdgcn_s_setprio(1); _Pragma("unroll") for (int m = 0; m < 4; ++m) _Pragma("unroll") for (int n = 0; n < 2; ++n) _Pragma("unroll") for (int k = 0; k < 2; ++k) \
;         acc[ai][bj][m][n] = __builtin_amdgcn_mfma_f32_16x16x32_bf16(Bt[n][k], At[m][k], acc[ai][bj][m][n], 0, 0, 0); __builtin_amdgcn_s_setprio(0); } while (0)
; #define PG8_WAIT_V(n) asm volatile("s_waitcnt vmcnt(" #n ")" ::: "memory")
; #define PG8_WAIT_L(n) asm volatile("s_waitcnt lgkmcnt(" #n ")" ::: "memory")
; template <class Epi, class Sched, bool ALIGN_EPI = false, bool SP2 = false>
; __device__ __forceinline__ void gemm_phase(PG8_LAS unsigned char* lds, const Gemm g, const Sched& S, const Epi& E) {
;     ...
;             const bool last = (t == nt - 2);
;             const char* a1 = cA + (size_t)(t + 1) * kstep;
;             const char* a2 = last ? nA : cA + (size_t)(t + 2) * kstep; const char* b2 = last ? nB : cB + (size_t)(t + 2) * kstep;
;             const char* a3 = a2 + kstep; const char* b3 = b2 + kstep;
;             if (last && has_next) S.a_ready(nxt);
;             if constexpr (SP2) {
;             PG8_LDB(B0, 0, 0); PG8_LDB(B1, 0, 1); PG8_SCHED; PG8_LDA(At, 0, 0); PG8_STAGE(PG8_SA(1, 1), a1 + hstepA, voffA);
;             PG8_WAIT_V(8); PG8_WAIT_L(0); PG8_BAR; PG8_MMA(0, 0, At, B0); PG8_MMA(0, 1, At, B1); PG8_BAR; PG8_SCHED;
;             PG8_LDA(At, 0, 1); PG8_STAGE(PG8_SB(0, 0), b2, voffB); PG8_STAGE(PG8_SB(0, 1), b2 + hstep, voffB); PG8_STAGE(PG8_SA(0, 0), a2, voffA);
;             PG8_WAIT_V(8); PG8_WAIT_L(0); PG8_BAR; PG8_MMA(1, 0, At, B0); PG8_MMA(1, 1, At, B1); PG8_BAR; PG8_SCHED;
.LBB0_1007:
	s_add_u32 s34, s46, 0xfffc0080
	s_addc_u32 s35, s47, -1
	s_add_i32 s67, 0, 0x10000
	s_cmp_eq_u32 s66, 12
	s_cselect_b32 s51, s37, s35
	s_cselect_b32 s50, s43, s34
	s_cselect_b32 s49, s27, s65
	s_cselect_b32 s48, s63, s64
	s_add_i32 s68, 0, 0x14000
	v_add_u32_e32 v142, s67, v196
	v_add_u32_e32 v158, s68, v196
	ds_read_b128 v[126:129], v142
	ds_read_b128 v[134:137], v142 offset:1024
	ds_read_b128 v[138:141], v142 offset:2048
	ds_read_b128 v[142:145], v142 offset:3072
	ds_read_b128 v[146:149], v158
	ds_read_b128 v[150:153], v158 offset:1024
	ds_read_b128 v[154:157], v158 offset:2048
	ds_read_b128 v[158:161], v158 offset:3072
	v_lshl_add_u64 v[212:213], s[46:47], 0, v[172:173]
	s_add_i32 m0, s45, 0xc000
	ds_read_b128 v[176:179], v198
	ds_read_b128 v[180:183], v198 offset:1024
	ds_read_b128 v[184:187], v198 offset:2048
	ds_read_b128 v[188:191], v198 offset:3072
	ds_read_b128 v[192:195], v198 offset:4096
	ds_read_b128 v[200:203], v198 offset:5120
	ds_read_b128 v[204:207], v198 offset:6144
	ds_read_b128 v[208:211], v198 offset:7168
	global_load_lds_dwordx4 v[212:213], off
	v_lshl_add_u64 v[212:213], s[46:47], 0, v[174:175]
	s_add_i32 m0, s45, 0xe000
	s_nop 0
	global_load_lds_dwordx4 v[212:213], off
	s_waitcnt vmcnt(8)
	s_waitcnt lgkmcnt(0)
	s_barrier
	s_waitcnt lgkmcnt(0)
	v_mfma_f32_16x16x32_bf16 v[130:133], v[126:129], v[176:179], v[130:133]
	v_mfma_f32_16x16x32_bf16 v[118:121], v[138:141], v[176:179], v[118:121]
	v_mfma_f32_16x16x32_bf16 v[110:113], v[126:129], v[184:187], v[110:113]
	v_mfma_f32_16x16x32_bf16 v[102:105], v[138:141], v[184:187], v[102:105]
	v_mfma_f32_16x16x32_bf16 v[94:97], v[126:129], v[192:195], v[94:97]
	v_mfma_f32_16x16x32_bf16 v[86:89], v[138:141], v[192:195], v[86:89]
	v_mfma_f32_16x16x32_bf16 v[78:81], v[126:129], v[204:207], v[78:81]
	v_mfma_f32_16x16x32_bf16 v[70:73], v[138:141], v[204:207], v[70:73]
	v_mfma_f32_16x16x32_bf16 v[130:133], v[134:137], v[180:183], v[130:133]
	v_mfma_f32_16x16x32_bf16 v[118:121], v[142:145], v[180:183], v[118:121]
	v_mfma_f32_16x16x32_bf16 v[110:113], v[134:137], v[188:191], v[110:113]
	v_mfma_f32_16x16x32_bf16 v[102:105], v[142:145], v[188:191], v[102:105]
	v_mfma_f32_16x16x32_bf16 v[94:97], v[134:137], v[200:203], v[94:97]
	v_mfma_f32_16x16x32_bf16 v[86:89], v[142:145], v[200:203], v[86:89]
	v_mfma_f32_16x16x32_bf16 v[78:81], v[134:137], v[208:211], v[78:81]
	v_mfma_f32_16x16x32_bf16 v[70:73], v[142:145], v[208:211], v[70:73]
	v_mfma_f32_16x16x32_bf16 v[122:125], v[146:149], v[176:179], v[122:125]
	v_mfma_f32_16x16x32_bf16 v[114:117], v[154:157], v[176:179], v[114:117]
	v_mfma_f32_16x16x32_bf16 v[106:109], v[146:149], v[184:187], v[106:109]
	v_mfma_f32_16x16x32_bf16 v[98:101], v[154:157], v[184:187], v[98:101]
	v_mfma_f32_16x16x32_bf16 v[90:93], v[146:149], v[192:195], v[90:93]
	v_mfma_f32_16x16x32_bf16 v[82:85], v[154:157], v[192:195], v[82:85]
	v_mfma_f32_16x16x32_bf16 v[74:77], v[146:149], v[204:207], v[74:77]
	v_mfma_f32_16x16x32_bf16 v[66:69], v[154:157], v[204:207], v[66:69]
	v_mfma_f32_16x16x32_bf16 v[122:125], v[150:153], v[180:183], v[122:125]
	v_mfma_f32_16x16x32_bf16 v[114:117], v[158:161], v[180:183], v[114:117]
	v_mfma_f32_16x16x32_bf16 v[106:109], v[150:153], v[188:191], v[106:109]
	v_mfma_f32_16x16x32_bf16 v[98:101], v[158:161], v[188:191], v[98:101]
	v_mfma_f32_16x16x32_bf16 v[90:93], v[150:153], v[200:203], v[90:93]
	v_mfma_f32_16x16x32_bf16 v[82:85], v[158:161], v[200:203], v[82:85]
	v_mfma_f32_16x16x32_bf16 v[74:77], v[150:153], v[208:211], v[74:77]
	v_mfma_f32_16x16x32_bf16 v[66:69], v[158:161], v[208:211], v[66:69]
	s_barrier
	s_add_i32 s34, s67, s22
	v_lshl_add_u64 v[212:213], s[48:49], 0, v[166:167]
	s_mov_b32 m0, s34
	ds_read_b128 v[176:179], v198 offset:16384
	ds_read_b128 v[180:183], v198 offset:17408
	ds_read_b128 v[184:187], v198 offset:18432
	ds_read_b128 v[188:191], v198 offset:19456
	ds_read_b128 v[192:195], v198 offset:20480
	ds_read_b128 v[200:203], v198 offset:21504
	ds_read_b128 v[204:207], v198 offset:22528
	ds_read_b128 v[208:211], v198 offset:23552
	global_load_lds_dwordx4 v[212:213], off
	s_add_i32 m0, s34, 0x2000
	s_add_u32 s34, s48, 0x40000
	v_lshl_add_u64 v[214:215], s[48:49], 0, v[162:163]
	s_addc_u32 s35, s49, 0
	s_add_i32 s67, s68, s22
	global_load_lds_dwordx4 v[214:215], off
	v_lshl_add_u64 v[216:217], s[34:35], 0, v[166:167]
	s_mov_b32 m0, s67
	v_lshl_add_u64 v[218:219], s[50:51], 0, v[164:165]
	global_load_lds_dwordx4 v[216:217], off
	v_lshl_add_u64 v[216:217], s[34:35], 0, v[162:163]
	s_add_i32 m0, s67, 0x2000
	s_nop 0
	global_load_lds_dwordx4 v[216:217], off
	v_lshl_add_u64 v[216:217], s[50:51], 0, v[168:169]
	s_mov_b32 m0, s45
	s_nop 0
	global_load_lds_dwordx4 v[216:217], off
	s_mov_b32 m0, s55
	s_nop 0
	global_load_lds_dwordx4 v[218:219], off
	s_waitcnt vmcnt(8)
	s_waitcnt lgkmcnt(0)
	s_barrier
; #define PG8_STAGE(bufoff, gbase, voff) do { _Pragma("unroll") for (int _i = 0; _i < 2; ++_i) \
;         __builtin_amdgcn_global_load_lds((const unsigned*)((const char*)(gbase) + (voff)[_i]), (PG8_LAS unsigned*)(lds + (bufoff) + ldsw + _i * 8192), 16, 0, 0); } while (0)
; #define PG8_LDA(dst, b, h) do { _Pragma("unroll") for (int m = 0; m < 4; ++m) _Pragma("unroll") for (int k = 0; k < 2; ++k) dst[m][k] = *(const PG8_LAS bf16x8*)(lds + PG8_SA(b, h) + aoff + m * 2048 + k * 1024); } while (0)
; #define PG8_LDB(dst, b, h) do { _Pragma("unroll") for (int n = 0; n < 2; ++n) _Pragma("unroll") for (int k = 0; k < 2; ++k) dst[n][k] = *(const PG8_LAS bf16x8*)(lds + PG8_SB(b, h) + boff + n * 2048 + k * 1024); } while (0)
; #define PG8_MMA(ai, bj, At, Bt) do { __builtin_amdgcn_s_setprio(1); _Pragma("unroll") for (int m = 0; m < 4; ++m) _Pragma("unroll") for (int n = 0; n < 2; ++n) _Pragma("unroll") for (int k = 0; k < 2; ++k) \
;         acc[ai][bj][m][n] = __builtin_amdgcn_mfma_f32_16x16x32_bf16(Bt[n][k], At[m][k], acc[ai][bj][m][n], 0, 0, 0); __builtin_amdgcn_s_setprio(0); } while (0)
; #define PG8_WAIT_V(n) asm volatile("s_waitcnt vmcnt(" #n ")" ::: "memory")
; #define PG8_WAIT_L(n) asm volatile("s_waitcnt lgkmcnt(" #n ")" ::: "memory")
; #define PG8_BAR __builtin_amdgcn_s_barrier()
; #define PG8_SCHED __builtin_amdgcn_sched_barrier(0)
; template <class Epi, class Sched, bool ALIGN_EPI = false, bool SP2 = false>
; __device__ __forceinline__ void gemm_phase(PG8_LAS unsigned char* lds, const Gemm g, const Sched& S, const Epi& E) {
;     ...
;             PG8_WAIT_V(8); PG8_WAIT_L(0); PG8_BAR; PG8_MMA(1, 0, At, B0); PG8_MMA(1, 1, At, B1); PG8_BAR; PG8_SCHED;
;             PG8_LDB(B0, 1, 0); PG8_LDB(B1, 1, 1); PG8_SCHED; PG8_LDA(At, 1, 0); PG8_STAGE(PG8_SA(0, 1), a2 + hstepA, voffA);
;             PG8_WAIT_V(8); PG8_WAIT_L(0); PG8_BAR; PG8_MMA(0, 0, At, B0); PG8_MMA(0, 1, At, B1); PG8_BAR; PG8_SCHED;
	s_waitcnt lgkmcnt(0)
	v_mfma_f32_16x16x32_bf16 v[62:65], v[126:129], v[176:179], v[62:65]
	v_mfma_f32_16x16x32_bf16 v[54:57], v[138:141], v[176:179], v[54:57]
	v_mfma_f32_16x16x32_bf16 v[46:49], v[126:129], v[184:187], v[46:49]
	v_mfma_f32_16x16x32_bf16 v[38:41], v[138:141], v[184:187], v[38:41]
	v_mfma_f32_16x16x32_bf16 v[30:33], v[126:129], v[192:195], v[30:33]
	v_mfma_f32_16x16x32_bf16 v[22:25], v[138:141], v[192:195], v[22:25]
	v_mfma_f32_16x16x32_bf16 v[14:17], v[126:129], v[204:207], v[14:17]
	v_mfma_f32_16x16x32_bf16 v[6:9], v[138:141], v[204:207], v[6:9]
	v_mfma_f32_16x16x32_bf16 v[62:65], v[134:137], v[180:183], v[62:65]
	v_mfma_f32_16x16x32_bf16 v[54:57], v[142:145], v[180:183], v[54:57]
	v_mfma_f32_16x16x32_bf16 v[46:49], v[134:137], v[188:191], v[46:49]
	v_mfma_f32_16x16x32_bf16 v[38:41], v[142:145], v[188:191], v[38:41]
	v_mfma_f32_16x16x32_bf16 v[30:33], v[134:137], v[200:203], v[30:33]
	v_mfma_f32_16x16x32_bf16 v[22:25], v[142:145], v[200:203], v[22:25]
	v_mfma_f32_16x16x32_bf16 v[14:17], v[134:137], v[208:211], v[14:17]
	v_mfma_f32_16x16x32_bf16 v[6:9], v[142:145], v[208:211], v[6:9]
	v_mfma_f32_16x16x32_bf16 v[58:61], v[146:149], v[176:179], v[58:61]
	v_mfma_f32_16x16x32_bf16 v[50:53], v[154:157], v[176:179], v[50:53]
	v_mfma_f32_16x16x32_bf16 v[42:45], v[146:149], v[184:187], v[42:45]
	v_mfma_f32_16x16x32_bf16 v[34:37], v[154:157], v[184:187], v[34:37]
	v_mfma_f32_16x16x32_bf16 v[26:29], v[146:149], v[192:195], v[26:29]
	v_mfma_f32_16x16x32_bf16 v[18:21], v[154:157], v[192:195], v[18:21]
	v_mfma_f32_16x16x32_bf16 v[10:13], v[146:149], v[204:207], v[10:13]
	v_mfma_f32_16x16x32_bf16 v[2:5], v[154:157], v[204:207], v[2:5]
	v_mfma_f32_16x16x32_bf16 v[58:61], v[150:153], v[180:183], v[58:61]
	v_mfma_f32_16x16x32_bf16 v[50:53], v[158:161], v[180:183], v[50:53]
	v_mfma_f32_16x16x32_bf16 v[42:45], v[150:153], v[188:191], v[42:45]
	v_mfma_f32_16x16x32_bf16 v[34:37], v[158:161], v[188:191], v[34:37]
	v_mfma_f32_16x16x32_bf16 v[26:29], v[150:153], v[200:203], v[26:29]
	v_mfma_f32_16x16x32_bf16 v[18:21], v[158:161], v[200:203], v[18:21]
	v_mfma_f32_16x16x32_bf16 v[10:13], v[150:153], v[208:211], v[10:13]
	v_mfma_f32_16x16x32_bf16 v[2:5], v[158:161], v[208:211], v[2:5]
	s_barrier
	s_add_i32 s67, 0, 0x18000
	s_add_i32 s68, 0, 0x1c000
	v_add_u32_e32 v142, s67, v196
	v_add_u32_e32 v158, s68, v196
	ds_read_b128 v[126:129], v142
	ds_read_b128 v[134:137], v142 offset:1024
	ds_read_b128 v[138:141], v142 offset:2048
	ds_read_b128 v[142:145], v142 offset:3072
	ds_read_b128 v[146:149], v158
	ds_read_b128 v[150:153], v158 offset:1024
	ds_read_b128 v[154:157], v158 offset:2048
	ds_read_b128 v[158:161], v158 offset:3072
	s_add_u32 s34, s50, 0x40000
	s_addc_u32 s35, s51, 0
	s_mov_b32 m0, s56
	v_lshl_add_u64 v[220:221], s[34:35], 0, v[168:169]
	ds_read_b128 v[176:179], v198 offset:32768
	ds_read_b128 v[180:183], v198 offset:33792
	ds_read_b128 v[184:187], v198 offset:34816
	ds_read_b128 v[188:191], v198 offset:35840
	ds_read_b128 v[192:195], v198 offset:36864
	ds_read_b128 v[200:203], v198 offset:37888
	ds_read_b128 v[204:207], v198 offset:38912
	ds_read_b128 v[208:211], v198 offset:39936
	global_load_lds_dwordx4 v[220:221], off
	v_lshl_add_u64 v[220:221], s[34:35], 0, v[164:165]
	s_mov_b32 m0, s57
	s_nop 0
	global_load_lds_dwordx4 v[220:221], off
	s_waitcnt vmcnt(8)
	s_waitcnt lgkmcnt(0)
	s_barrier
	s_waitcnt lgkmcnt(0)
	v_mfma_f32_16x16x32_bf16 v[130:133], v[126:129], v[176:179], v[130:133]
	v_mfma_f32_16x16x32_bf16 v[118:121], v[138:141], v[176:179], v[118:121]
	v_mfma_f32_16x16x32_bf16 v[110:113], v[126:129], v[184:187], v[110:113]
	v_mfma_f32_16x16x32_bf16 v[102:105], v[138:141], v[184:187], v[102:105]
	v_mfma_f32_16x16x32_bf16 v[94:97], v[126:129], v[192:195], v[94:97]
	v_mfma_f32_16x16x32_bf16 v[86:89], v[138:141], v[192:195], v[86:89]
	v_mfma_f32_16x16x32_bf16 v[78:81], v[126:129], v[204:207], v[78:81]
	v_mfma_f32_16x16x32_bf16 v[70:73], v[138:141], v[204:207], v[70:73]
	v_mfma_f32_16x16x32_bf16 v[130:133], v[134:137], v[180:183], v[130:133]
	v_mfma_f32_16x16x32_bf16 v[118:121], v[142:145], v[180:183], v[118:121]
	v_mfma_f32_16x16x32_bf16 v[110:113], v[134:137], v[188:191], v[110:113]
	v_mfma_f32_16x16x32_bf16 v[102:105], v[142:145], v[188:191], v[102:105]
	v_mfma_f32_16x16x32_bf16 v[94:97], v[134:137], v[200:203], v[94:97]
	v_mfma_f32_16x16x32_bf16 v[86:89], v[142:145], v[200:203], v[86:89]
	v_mfma_f32_16x16x32_bf16 v[78:81], v[134:137], v[208:211], v[78:81]
	v_mfma_f32_16x16x32_bf16 v[70:73], v[142:145], v[208:211], v[70:73]
	v_mfma_f32_16x16x32_bf16 v[122:125], v[146:149], v[176:179], v[122:125]
	v_mfma_f32_16x16x32_bf16 v[114:117], v[154:157], v[176:179], v[114:117]
	v_mfma_f32_16x16x32_bf16 v[106:109], v[146:149], v[184:187], v[106:109]
	v_mfma_f32_16x16x32_bf16 v[98:101], v[154:157], v[184:187], v[98:101]
	v_mfma_f32_16x16x32_bf16 v[90:93], v[146:149], v[192:195], v[90:93]
	v_mfma_f32_16x16x32_bf16 v[82:85], v[154:157], v[192:195], v[82:85]
	v_mfma_f32_16x16x32_bf16 v[74:77], v[146:149], v[204:207], v[74:77]
	v_mfma_f32_16x16x32_bf16 v[66:69], v[154:157], v[204:207], v[66:69]
	v_mfma_f32_16x16x32_bf16 v[122:125], v[150:153], v[180:183], v[122:125]
	v_mfma_f32_16x16x32_bf16 v[114:117], v[158:161], v[180:183], v[114:117]
	v_mfma_f32_16x16x32_bf16 v[106:109], v[150:153], v[188:191], v[106:109]
	v_mfma_f32_16x16x32_bf16 v[98:101], v[158:161], v[188:191], v[98:101]
	v_mfma_f32_16x16x32_bf16 v[90:93], v[150:153], v[200:203], v[90:93]
	v_mfma_f32_16x16x32_bf16 v[82:85], v[158:161], v[200:203], v[82:85]
	v_mfma_f32_16x16x32_bf16 v[74:77], v[150:153], v[208:211], v[74:77]
	v_mfma_f32_16x16x32_bf16 v[66:69], v[158:161], v[208:211], v[66:69]
	s_barrier
; #define PG8_STAGE(bufoff, gbase, voff) do { _Pragma("unroll") for (int _i = 0; _i < 2; ++_i) \
;         __builtin_amdgcn_global_load_lds((const unsigned*)((const char*)(gbase) + (voff)[_i]), (PG8_LAS unsigned*)(lds + (bufoff) + ldsw + _i * 8192), 16, 0, 0); } while (0)
; #define PG8_LDA(dst, b, h) do { _Pragma("unroll") for (int m = 0; m < 4; ++m) _Pragma("unroll") for (int k = 0; k < 2; ++k) dst[m][k] = *(const PG8_LAS bf16x8*)(lds + PG8_SA(b, h) + aoff + m * 2048 + k * 1024); } while (0)
; #define PG8_MMA(ai, bj, At, Bt) do { __builtin_amdgcn_s_setprio(1); _Pragma("unroll") for (int m = 0; m < 4; ++m) _Pragma("unroll") for (int n = 0; n < 2; ++n) _Pragma("unroll") for (int k = 0; k < 2; ++k) \
;         acc[ai][bj][m][n] = __builtin_amdgcn_mfma_f32_16x16x32_bf16(Bt[n][k], At[m][k], acc[ai][bj][m][n], 0, 0, 0); __builtin_amdgcn_s_setprio(0); } while (0)
; #define PG8_WAIT_V(n) asm volatile("s_waitcnt vmcnt(" #n ")" ::: "memory")
; #define PG8_WAIT_L(n) asm volatile("s_waitcnt lgkmcnt(" #n ")" ::: "memory")
; #define PG8_BAR __builtin_amdgcn_s_barrier()
; #define PG8_SCHED __builtin_amdgcn_sched_barrier(0)
; template <class Epi, class Sched, bool ALIGN_EPI = false, bool SP2 = false>
; __device__ __forceinline__ void gemm_phase(PG8_LAS unsigned char* lds, const Gemm g, const Sched& S, const Epi& E) {
;     ...
;             PG8_LDA(At, 1, 1); PG8_STAGE(PG8_SB(1, 0), b3, voffB); PG8_STAGE(PG8_SB(1, 1), b3 + hstep, voffB); PG8_STAGE(PG8_SA(1, 0), a3, voffA);
;             PG8_WAIT_V(8); PG8_WAIT_L(0); PG8_BAR; PG8_MMA(1, 0, At, B0); PG8_MMA(1, 1, At, B1); PG8_BAR; PG8_SCHED;
;     ...
;         if constexpr (ALIGN_EPI) { if (wr == 0) PG8_BAR; }
	s_add_i32 s34, s67, s22
	v_lshl_add_u64 v[212:213], v[212:213], 0, s[12:13]
	s_mov_b32 m0, s34
	ds_read_b128 v[176:179], v198 offset:49152
	ds_read_b128 v[180:183], v198 offset:50176
	ds_read_b128 v[184:187], v198 offset:51200
	ds_read_b128 v[188:191], v198 offset:52224
	ds_read_b128 v[192:195], v198 offset:53248
	ds_read_b128 v[200:203], v198 offset:54272
	ds_read_b128 v[204:207], v198 offset:55296
	ds_read_b128 v[208:211], v198 offset:56320
	global_load_lds_dwordx4 v[212:213], off
	s_add_i32 m0, s34, 0x2000
	s_add_u32 s34, s48, 0x40080
	v_lshl_add_u64 v[212:213], v[214:215], 0, s[12:13]
	s_addc_u32 s35, s49, 0
	s_add_i32 s48, s68, s22
	global_load_lds_dwordx4 v[212:213], off
	v_lshl_add_u64 v[212:213], s[34:35], 0, v[166:167]
	s_mov_b32 m0, s48
	s_nop 0
	global_load_lds_dwordx4 v[212:213], off
	v_lshl_add_u64 v[212:213], s[34:35], 0, v[162:163]
	s_add_i32 m0, s48, 0x2000
	s_nop 0
	global_load_lds_dwordx4 v[212:213], off
	v_lshl_add_u64 v[212:213], v[216:217], 0, s[12:13]
	s_mov_b32 m0, s58
	s_nop 0
	global_load_lds_dwordx4 v[212:213], off
	v_lshl_add_u64 v[212:213], v[218:219], 0, s[12:13]
	s_mov_b32 m0, s59
	s_nop 0
	global_load_lds_dwordx4 v[212:213], off
	s_waitcnt vmcnt(8)
	s_waitcnt lgkmcnt(0)
	s_barrier
	s_waitcnt lgkmcnt(0)
	v_mfma_f32_16x16x32_bf16 v[62:65], v[126:129], v[176:179], v[62:65]
	v_mfma_f32_16x16x32_bf16 v[54:57], v[138:141], v[176:179], v[54:57]
	v_mfma_f32_16x16x32_bf16 v[46:49], v[126:129], v[184:187], v[46:49]
	v_mfma_f32_16x16x32_bf16 v[38:41], v[138:141], v[184:187], v[38:41]
	v_mfma_f32_16x16x32_bf16 v[30:33], v[126:129], v[192:195], v[30:33]
	v_mfma_f32_16x16x32_bf16 v[22:25], v[138:141], v[192:195], v[22:25]
	v_mfma_f32_16x16x32_bf16 v[14:17], v[126:129], v[204:207], v[14:17]
	v_mfma_f32_16x16x32_bf16 v[6:9], v[138:141], v[204:207], v[6:9]
	v_mfma_f32_16x16x32_bf16 v[62:65], v[134:137], v[180:183], v[62:65]
	v_mfma_f32_16x16x32_bf16 v[54:57], v[142:145], v[180:183], v[54:57]
	v_mfma_f32_16x16x32_bf16 v[46:49], v[134:137], v[188:191], v[46:49]
	v_mfma_f32_16x16x32_bf16 v[38:41], v[142:145], v[188:191], v[38:41]
	v_mfma_f32_16x16x32_bf16 v[30:33], v[134:137], v[200:203], v[30:33]
	v_mfma_f32_16x16x32_bf16 v[22:25], v[142:145], v[200:203], v[22:25]
	v_mfma_f32_16x16x32_bf16 v[14:17], v[134:137], v[208:211], v[14:17]
	v_mfma_f32_16x16x32_bf16 v[6:9], v[142:145], v[208:211], v[6:9]
	v_mfma_f32_16x16x32_bf16 v[58:61], v[146:149], v[176:179], v[58:61]
	v_mfma_f32_16x16x32_bf16 v[50:53], v[154:157], v[176:179], v[50:53]
	v_mfma_f32_16x16x32_bf16 v[42:45], v[146:149], v[184:187], v[42:45]
	v_mfma_f32_16x16x32_bf16 v[34:37], v[154:157], v[184:187], v[34:37]
	v_mfma_f32_16x16x32_bf16 v[26:29], v[146:149], v[192:195], v[26:29]
	v_mfma_f32_16x16x32_bf16 v[18:21], v[154:157], v[192:195], v[18:21]
	v_mfma_f32_16x16x32_bf16 v[10:13], v[146:149], v[204:207], v[10:13]
	v_mfma_f32_16x16x32_bf16 v[2:5], v[154:157], v[204:207], v[2:5]
	v_mfma_f32_16x16x32_bf16 v[58:61], v[150:153], v[180:183], v[58:61]
	v_mfma_f32_16x16x32_bf16 v[50:53], v[158:161], v[180:183], v[50:53]
	v_mfma_f32_16x16x32_bf16 v[42:45], v[150:153], v[188:191], v[42:45]
	v_mfma_f32_16x16x32_bf16 v[34:37], v[158:161], v[188:191], v[34:37]
	v_mfma_f32_16x16x32_bf16 v[26:29], v[150:153], v[200:203], v[26:29]
	v_mfma_f32_16x16x32_bf16 v[18:21], v[158:161], v[200:203], v[18:21]
	v_mfma_f32_16x16x32_bf16 v[10:13], v[150:153], v[208:211], v[10:13]
	v_mfma_f32_16x16x32_bf16 v[2:5], v[158:161], v[208:211], v[2:5]
	s_barrier
	s_add_i32 s66, s66, 2
	s_add_u32 s46, s46, 0x100
	s_addc_u32 s47, s47, 0
	s_add_u32 s64, s64, 0x100
	s_addc_u32 s65, s65, 0
	s_cmp_gt_u32 s66, 13
	s_cbranch_scc0 .LBB0_1007
	s_and_b64 vcc, exec, s[20:21]
	s_cbranch_vccz .LBB0_1010
	s_barrier

; #define PG8_STAGE(bufoff, gbase, voff) do { _Pragma("unroll") for (int _i = 0; _i < 2; ++_i) \
;         __builtin_amdgcn_global_load_lds((const unsigned*)((const char*)(gbase) + (voff)[_i]), (PG8_LAS unsigned*)(lds + (bufoff) + ldsw + _i * 8192), 16, 0, 0); } while (0)
; #define PG8_LDA(dst, b, h) do { _Pragma("unroll") for (int m = 0; m < 4; ++m) _Pragma("unroll") for (int k = 0; k < 2; ++k) dst[m][k] = *(const PG8_LAS bf16x8*)(lds + PG8_SA(b, h) + aoff + m * 2048 + k * 1024); } while (0)
; #define PG8_LDB(dst, b, h) do { _Pragma("unroll") for (int n = 0; n < 2; ++n) _Pragma("unroll") for (int k = 0; k < 2; ++k) dst[n][k] = *(const PG8_LAS bf16x8*)(lds + PG8_SB(b, h) + boff + n * 2048 + k * 1024); } while (0)
; #define PG8_WAIT_V(n) asm volatile("s_waitcnt vmcnt(" #n ")" ::: "memory")
; #define PG8_WAIT_L(n) asm volatile("s_waitcnt lgkmcnt(" #n ")" ::: "memory")
; #define PG8_BAR __builtin_amdgcn_s_barrier()
; #define PG8_SCHED __builtin_amdgcn_sched_barrier(0)
; template <class Epi, class Sched, bool ALIGN_EPI = false, bool SP2 = false>
; __device__ __forceinline__ void gemm_phase(PG8_LAS unsigned char* lds, const Gemm g, const Sched& S, const Epi& E) {
;     ...
;         const char* nA = has_next ? (const char*)g.A + (size_t)nxt.pm * tstepA + (size_t)(nxt.pn >> 2) * g.aselb : cA; const char* nB = has_next ? (const char*)g.Bt + (size_t)nxt.pn * tstep : cB;
;         for (int t = 0; t < nt; t += 2) {
;             if constexpr (Epi::MID) { if (t == (nt >> 1)) E.mid(acc, cur, wr, wc, fr, fq); }
;             const bool last = (t == nt - 2);
;             const char* a1 = cA + (size_t)(t + 1) * kstep;
;             const char* a2 = last ? nA : cA + (size_t)(t + 2) * kstep; const char* b2 = last ? nB : cB + (size_t)(t + 2) * kstep;
;             const char* a3 = a2 + kstep; const char* b3 = b2 + kstep;
;             if (last && has_next) S.a_ready(nxt);
;             if constexpr (SP2) {
;             PG8_LDB(B0, 0, 0); PG8_LDB(B1, 0, 1); PG8_SCHED; PG8_LDA(At, 0, 0); PG8_STAGE(PG8_SA(1, 1), a1 + hstepA, voffA);
;             PG8_WAIT_V(8); PG8_WAIT_L(0); PG8_BAR; PG8_MMA(0, 0, At, B0); PG8_MMA(0, 1, At, B1); PG8_BAR; PG8_SCHED;
;             PG8_LDA(At, 0, 1); PG8_STAGE(PG8_SB(0, 0), b2, voffB); PG8_STAGE(PG8_SB(0, 1), b2 + hstep, voffB); PG8_STAGE(PG8_SA(0, 0), a2, voffA);
.LBB0_1033:
	s_add_i32 s71, s46, 2
	s_add_u32 s34, s38, 0x80
	s_addc_u32 s35, s39, 0
	s_add_i32 s74, 0, 0x10000
	s_cmp_eq_u32 s64, s46
	s_cselect_b32 s47, s43, s35
	s_cselect_b32 s46, s42, s34
	s_cselect_b32 s73, s45, s49
	s_cselect_b32 s72, s44, s48
	s_add_i32 s34, 0, 0x14000
	v_add_u32_e32 v102, s74, v236
	v_add_u32_e32 v150, s34, v236
	ds_read_b128 v[66:69], v102
	ds_read_b128 v[78:81], v102 offset:1024
	ds_read_b128 v[90:93], v102 offset:2048
	ds_read_b128 v[102:105], v102 offset:3072
	ds_read_b128 v[114:117], v150
	ds_read_b128 v[126:129], v150 offset:1024
	ds_read_b128 v[138:141], v150 offset:2048
	ds_read_b128 v[150:153], v150 offset:3072
	v_lshl_add_u64 v[208:209], s[38:39], 0, v[200:201]
	s_add_i32 m0, s56, 0xc000
	ds_read_b128 v[162:165], v238
	ds_read_b128 v[166:169], v238 offset:1024
	ds_read_b128 v[170:173], v238 offset:2048
	ds_read_b128 v[174:177], v238 offset:3072
	ds_read_b128 v[178:181], v238 offset:4096
	ds_read_b128 v[182:185], v238 offset:5120
	ds_read_b128 v[186:189], v238 offset:6144
	ds_read_b128 v[204:207], v238 offset:7168
	global_load_lds_dwordx4 v[208:209], off
	v_lshl_add_u64 v[208:209], s[38:39], 0, v[202:203]
	s_add_i32 m0, s56, 0xe000
	s_nop 0
	global_load_lds_dwordx4 v[208:209], off
	s_waitcnt vmcnt(8)
	s_waitcnt lgkmcnt(0)
	s_barrier
	s_waitcnt lgkmcnt(0)
	v_mfma_f32_16x16x32_bf16 v[158:161], v[66:69], v[162:165], v[158:161]
	v_mfma_f32_16x16x32_bf16 v[154:157], v[90:93], v[162:165], v[154:157]
	v_mfma_f32_16x16x32_bf16 v[134:137], v[66:69], v[170:173], v[134:137]
	v_mfma_f32_16x16x32_bf16 v[130:133], v[90:93], v[170:173], v[130:133]
	v_mfma_f32_16x16x32_bf16 v[110:113], v[66:69], v[178:181], v[110:113]
	v_mfma_f32_16x16x32_bf16 v[106:109], v[90:93], v[178:181], v[106:109]
	v_mfma_f32_16x16x32_bf16 v[86:89], v[66:69], v[186:189], v[86:89]
	v_mfma_f32_16x16x32_bf16 v[82:85], v[90:93], v[186:189], v[82:85]
	v_mfma_f32_16x16x32_bf16 v[158:161], v[78:81], v[166:169], v[158:161]
	v_mfma_f32_16x16x32_bf16 v[154:157], v[102:105], v[166:169], v[154:157]
	v_mfma_f32_16x16x32_bf16 v[134:137], v[78:81], v[174:177], v[134:137]
	v_mfma_f32_16x16x32_bf16 v[130:133], v[102:105], v[174:177], v[130:133]
	v_mfma_f32_16x16x32_bf16 v[110:113], v[78:81], v[182:185], v[110:113]
	v_mfma_f32_16x16x32_bf16 v[106:109], v[102:105], v[182:185], v[106:109]
	v_mfma_f32_16x16x32_bf16 v[86:89], v[78:81], v[204:207], v[86:89]
	v_mfma_f32_16x16x32_bf16 v[82:85], v[102:105], v[204:207], v[82:85]
	v_mfma_f32_16x16x32_bf16 v[146:149], v[114:117], v[162:165], v[146:149]
	v_mfma_f32_16x16x32_bf16 v[142:145], v[138:141], v[162:165], v[142:145]
	v_mfma_f32_16x16x32_bf16 v[122:125], v[114:117], v[170:173], v[122:125]
	v_mfma_f32_16x16x32_bf16 v[118:121], v[138:141], v[170:173], v[118:121]
	v_mfma_f32_16x16x32_bf16 v[98:101], v[114:117], v[178:181], v[98:101]
	v_mfma_f32_16x16x32_bf16 v[94:97], v[138:141], v[178:181], v[94:97]
	v_mfma_f32_16x16x32_bf16 v[74:77], v[114:117], v[186:189], v[74:77]
	v_mfma_f32_16x16x32_bf16 v[70:73], v[138:141], v[186:189], v[70:73]
	v_mfma_f32_16x16x32_bf16 v[146:149], v[126:129], v[166:169], v[146:149]
	v_mfma_f32_16x16x32_bf16 v[142:145], v[150:153], v[166:169], v[142:145]
	v_mfma_f32_16x16x32_bf16 v[122:125], v[126:129], v[174:177], v[122:125]
	v_mfma_f32_16x16x32_bf16 v[118:121], v[150:153], v[174:177], v[118:121]
	v_mfma_f32_16x16x32_bf16 v[98:101], v[126:129], v[182:185], v[98:101]
	v_mfma_f32_16x16x32_bf16 v[94:97], v[150:153], v[182:185], v[94:97]
	v_mfma_f32_16x16x32_bf16 v[74:77], v[126:129], v[204:207], v[74:77]
	v_mfma_f32_16x16x32_bf16 v[70:73], v[150:153], v[204:207], v[70:73]
	s_barrier
	s_add_i32 s35, s74, s53
	v_lshl_add_u64 v[208:209], s[72:73], 0, v[192:193]
	s_mov_b32 m0, s35
	ds_read_b128 v[162:165], v238 offset:16384
	ds_read_b128 v[166:169], v238 offset:17408
	ds_read_b128 v[170:173], v238 offset:18432
	ds_read_b128 v[174:177], v238 offset:19456
	ds_read_b128 v[178:181], v238 offset:20480
	ds_read_b128 v[182:185], v238 offset:21504
	ds_read_b128 v[186:189], v238 offset:22528
	ds_read_b128 v[204:207], v238 offset:23552
	global_load_lds_dwordx4 v[208:209], off
	s_add_i32 m0, s35, 0x2000
	v_lshl_add_u64 v[210:211], s[72:73], 0, v[196:197]
	s_add_u32 s72, s72, s4
	s_addc_u32 s73, s73, 0
	s_add_i32 s34, s34, s53
	global_load_lds_dwordx4 v[210:211], off
	v_lshl_add_u64 v[212:213], s[72:73], 0, v[192:193]
	s_mov_b32 m0, s34
	v_lshl_add_u64 v[214:215], s[72:73], 0, v[196:197]
	global_load_lds_dwordx4 v[212:213], off
	s_add_i32 m0, s34, 0x2000
	v_lshl_add_u64 v[216:217], s[46:47], 0, v[190:191]
	global_load_lds_dwordx4 v[214:215], off
	s_mov_b32 m0, s56
	v_lshl_add_u64 v[218:219], s[46:47], 0, v[194:195]
	global_load_lds_dwordx4 v[216:217], off
	s_mov_b32 m0, s57
	s_nop 0
	global_load_lds_dwordx4 v[218:219], off
	s_waitcnt vmcnt(8)
	s_waitcnt lgkmcnt(0)
	s_barrier
; #define PG8_STAGE(bufoff, gbase, voff) do { _Pragma("unroll") for (int _i = 0; _i < 2; ++_i) \
;         __builtin_amdgcn_global_load_lds((const unsigned*)((const char*)(gbase) + (voff)[_i]), (PG8_LAS unsigned*)(lds + (bufoff) + ldsw + _i * 8192), 16, 0, 0); } while (0)
; #define PG8_LDA(dst, b, h) do { _Pragma("unroll") for (int m = 0; m < 4; ++m) _Pragma("unroll") for (int k = 0; k < 2; ++k) dst[m][k] = *(const PG8_LAS bf16x8*)(lds + PG8_SA(b, h) + aoff + m * 2048 + k * 1024); } while (0)
; #define PG8_LDB(dst, b, h) do { _Pragma("unroll") for (int n = 0; n < 2; ++n) _Pragma("unroll") for (int k = 0; k < 2; ++k) dst[n][k] = *(const PG8_LAS bf16x8*)(lds + PG8_SB(b, h) + boff + n * 2048 + k * 1024); } while (0)
; #define PG8_MMA(ai, bj, At, Bt) do { __builtin_amdgcn_s_setprio(1); _Pragma("unroll") for (int m = 0; m < 4; ++m) _Pragma("unroll") for (int n = 0; n < 2; ++n) _Pragma("unroll") for (int k = 0; k < 2; ++k) \
;         acc[ai][bj][m][n] = __builtin_amdgcn_mfma_f32_16x16x32_bf16(Bt[n][k], At[m][k], acc[ai][bj][m][n], 0, 0, 0); __builtin_amdgcn_s_setprio(0); } while (0)
; #define PG8_WAIT_V(n) asm volatile("s_waitcnt vmcnt(" #n ")" ::: "memory")
; #define PG8_WAIT_L(n) asm volatile("s_waitcnt lgkmcnt(" #n ")" ::: "memory")
; #define PG8_BAR __builtin_amdgcn_s_barrier()
; #define PG8_SCHED __builtin_amdgcn_sched_barrier(0)
; template <class Epi, class Sched, bool ALIGN_EPI = false, bool SP2 = false>
; __device__ __forceinline__ void gemm_phase(PG8_LAS unsigned char* lds, const Gemm g, const Sched& S, const Epi& E) {
;     ...
;             PG8_WAIT_V(8); PG8_WAIT_L(0); PG8_BAR; PG8_MMA(1, 0, At, B0); PG8_MMA(1, 1, At, B1); PG8_BAR; PG8_SCHED;
;             PG8_LDB(B0, 1, 0); PG8_LDB(B1, 1, 1); PG8_SCHED; PG8_LDA(At, 1, 0); PG8_STAGE(PG8_SA(0, 1), a2 + hstepA, voffA);
;             PG8_WAIT_V(8); PG8_WAIT_L(0); PG8_BAR; PG8_MMA(0, 0, At, B0); PG8_MMA(0, 1, At, B1); PG8_BAR; PG8_SCHED;
	s_waitcnt lgkmcnt(0)
	v_mfma_f32_16x16x32_bf16 v[62:65], v[66:69], v[162:165], v[62:65]
	v_mfma_f32_16x16x32_bf16 v[58:61], v[90:93], v[162:165], v[58:61]
	v_mfma_f32_16x16x32_bf16 v[46:49], v[66:69], v[170:173], v[46:49]
	v_mfma_f32_16x16x32_bf16 v[42:45], v[90:93], v[170:173], v[42:45]
	v_mfma_f32_16x16x32_bf16 v[30:33], v[66:69], v[178:181], v[30:33]
	v_mfma_f32_16x16x32_bf16 v[26:29], v[90:93], v[178:181], v[26:29]
	v_mfma_f32_16x16x32_bf16 v[14:17], v[66:69], v[186:189], v[14:17]
	v_mfma_f32_16x16x32_bf16 v[10:13], v[90:93], v[186:189], v[10:13]
	v_mfma_f32_16x16x32_bf16 v[62:65], v[78:81], v[166:169], v[62:65]
	v_mfma_f32_16x16x32_bf16 v[58:61], v[102:105], v[166:169], v[58:61]
	v_mfma_f32_16x16x32_bf16 v[46:49], v[78:81], v[174:177], v[46:49]
	v_mfma_f32_16x16x32_bf16 v[42:45], v[102:105], v[174:177], v[42:45]
	v_mfma_f32_16x16x32_bf16 v[30:33], v[78:81], v[182:185], v[30:33]
	v_mfma_f32_16x16x32_bf16 v[26:29], v[102:105], v[182:185], v[26:29]
	v_mfma_f32_16x16x32_bf16 v[14:17], v[78:81], v[204:207], v[14:17]
	v_mfma_f32_16x16x32_bf16 v[10:13], v[102:105], v[204:207], v[10:13]
	v_mfma_f32_16x16x32_bf16 v[54:57], v[114:117], v[162:165], v[54:57]
	v_mfma_f32_16x16x32_bf16 v[50:53], v[138:141], v[162:165], v[50:53]
	v_mfma_f32_16x16x32_bf16 v[38:41], v[114:117], v[170:173], v[38:41]
	v_mfma_f32_16x16x32_bf16 v[34:37], v[138:141], v[170:173], v[34:37]
	v_mfma_f32_16x16x32_bf16 v[22:25], v[114:117], v[178:181], v[22:25]
	v_mfma_f32_16x16x32_bf16 v[18:21], v[138:141], v[178:181], v[18:21]
	v_mfma_f32_16x16x32_bf16 v[6:9], v[114:117], v[186:189], v[6:9]
	v_mfma_f32_16x16x32_bf16 v[2:5], v[138:141], v[186:189], v[2:5]
	v_mfma_f32_16x16x32_bf16 v[54:57], v[126:129], v[166:169], v[54:57]
	v_mfma_f32_16x16x32_bf16 v[50:53], v[150:153], v[166:169], v[50:53]
	v_mfma_f32_16x16x32_bf16 v[38:41], v[126:129], v[174:177], v[38:41]
	v_mfma_f32_16x16x32_bf16 v[34:37], v[150:153], v[174:177], v[34:37]
	v_mfma_f32_16x16x32_bf16 v[22:25], v[126:129], v[182:185], v[22:25]
	v_mfma_f32_16x16x32_bf16 v[18:21], v[150:153], v[182:185], v[18:21]
	v_mfma_f32_16x16x32_bf16 v[6:9], v[126:129], v[204:207], v[6:9]
	v_mfma_f32_16x16x32_bf16 v[2:5], v[150:153], v[204:207], v[2:5]
	s_barrier
	s_add_i32 s34, 0, 0x18000
	s_add_i32 s35, 0, 0x1c000
	v_add_u32_e32 v102, s34, v236
	v_add_u32_e32 v150, s35, v236
	ds_read_b128 v[66:69], v102
	ds_read_b128 v[78:81], v102 offset:1024
	ds_read_b128 v[90:93], v102 offset:2048
	ds_read_b128 v[102:105], v102 offset:3072
	ds_read_b128 v[114:117], v150
	ds_read_b128 v[126:129], v150 offset:1024
	ds_read_b128 v[138:141], v150 offset:2048
	ds_read_b128 v[150:153], v150 offset:3072
	s_add_u32 s46, s46, s4
	s_addc_u32 s47, s47, 0
	s_mov_b32 m0, s58
	v_lshl_add_u64 v[220:221], s[46:47], 0, v[190:191]
	ds_read_b128 v[162:165], v238 offset:32768
	ds_read_b128 v[166:169], v238 offset:33792
	ds_read_b128 v[170:173], v238 offset:34816
	ds_read_b128 v[174:177], v238 offset:35840
	ds_read_b128 v[178:181], v238 offset:36864
	ds_read_b128 v[182:185], v238 offset:37888
	ds_read_b128 v[186:189], v238 offset:38912
	ds_read_b128 v[204:207], v238 offset:39936
	global_load_lds_dwordx4 v[220:221], off
	v_lshl_add_u64 v[220:221], s[46:47], 0, v[194:195]
	s_mov_b32 m0, s59
	s_nop 0
	global_load_lds_dwordx4 v[220:221], off
	s_waitcnt vmcnt(8)
	s_waitcnt lgkmcnt(0)
	s_barrier
	s_waitcnt lgkmcnt(0)
	v_mfma_f32_16x16x32_bf16 v[158:161], v[66:69], v[162:165], v[158:161]
	v_mfma_f32_16x16x32_bf16 v[154:157], v[90:93], v[162:165], v[154:157]
	v_mfma_f32_16x16x32_bf16 v[134:137], v[66:69], v[170:173], v[134:137]
	v_mfma_f32_16x16x32_bf16 v[130:133], v[90:93], v[170:173], v[130:133]
	v_mfma_f32_16x16x32_bf16 v[110:113], v[66:69], v[178:181], v[110:113]
	v_mfma_f32_16x16x32_bf16 v[106:109], v[90:93], v[178:181], v[106:109]
	v_mfma_f32_16x16x32_bf16 v[86:89], v[66:69], v[186:189], v[86:89]
	v_mfma_f32_16x16x32_bf16 v[82:85], v[90:93], v[186:189], v[82:85]
	v_mfma_f32_16x16x32_bf16 v[158:161], v[78:81], v[166:169], v[158:161]
	v_mfma_f32_16x16x32_bf16 v[154:157], v[102:105], v[166:169], v[154:157]
	v_mfma_f32_16x16x32_bf16 v[134:137], v[78:81], v[174:177], v[134:137]
	v_mfma_f32_16x16x32_bf16 v[130:133], v[102:105], v[174:177], v[130:133]
	v_mfma_f32_16x16x32_bf16 v[110:113], v[78:81], v[182:185], v[110:113]
	v_mfma_f32_16x16x32_bf16 v[106:109], v[102:105], v[182:185], v[106:109]
	v_mfma_f32_16x16x32_bf16 v[86:89], v[78:81], v[204:207], v[86:89]
	v_mfma_f32_16x16x32_bf16 v[82:85], v[102:105], v[204:207], v[82:85]
	v_mfma_f32_16x16x32_bf16 v[146:149], v[114:117], v[162:165], v[146:149]
	v_mfma_f32_16x16x32_bf16 v[142:145], v[138:141], v[162:165], v[142:145]
	v_mfma_f32_16x16x32_bf16 v[122:125], v[114:117], v[170:173], v[122:125]
	v_mfma_f32_16x16x32_bf16 v[118:121], v[138:141], v[170:173], v[118:121]
	v_mfma_f32_16x16x32_bf16 v[98:101], v[114:117], v[178:181], v[98:101]
	v_mfma_f32_16x16x32_bf16 v[94:97], v[138:141], v[178:181], v[94:97]
	v_mfma_f32_16x16x32_bf16 v[74:77], v[114:117], v[186:189], v[74:77]
	v_mfma_f32_16x16x32_bf16 v[70:73], v[138:141], v[186:189], v[70:73]
	v_mfma_f32_16x16x32_bf16 v[146:149], v[126:129], v[166:169], v[146:149]
	v_mfma_f32_16x16x32_bf16 v[142:145], v[150:153], v[166:169], v[142:145]
	v_mfma_f32_16x16x32_bf16 v[122:125], v[126:129], v[174:177], v[122:125]
	v_mfma_f32_16x16x32_bf16 v[118:121], v[150:153], v[174:177], v[118:121]
	v_mfma_f32_16x16x32_bf16 v[98:101], v[126:129], v[182:185], v[98:101]
	v_mfma_f32_16x16x32_bf16 v[94:97], v[150:153], v[182:185], v[94:97]
	v_mfma_f32_16x16x32_bf16 v[74:77], v[126:129], v[204:207], v[74:77]
	v_mfma_f32_16x16x32_bf16 v[70:73], v[150:153], v[204:207], v[70:73]
	s_barrier
; #define PG8_STAGE(bufoff, gbase, voff) do { _Pragma("unroll") for (int _i = 0; _i < 2; ++_i) \
;         __builtin_amdgcn_global_load_lds((const unsigned*)((const char*)(gbase) + (voff)[_i]), (PG8_LAS unsigned*)(lds + (bufoff) + ldsw + _i * 8192), 16, 0, 0); } while (0)
; #define PG8_LDA(dst, b, h) do { _Pragma("unroll") for (int m = 0; m < 4; ++m) _Pragma("unroll") for (int k = 0; k < 2; ++k) dst[m][k] = *(const PG8_LAS bf16x8*)(lds + PG8_SA(b, h) + aoff + m * 2048 + k * 1024); } while (0)
; #define PG8_MMA(ai, bj, At, Bt) do { __builtin_amdgcn_s_setprio(1); _Pragma("unroll") for (int m = 0; m < 4; ++m) _Pragma("unroll") for (int n = 0; n < 2; ++n) _Pragma("unroll") for (int k = 0; k < 2; ++k) \
;         acc[ai][bj][m][n] = __builtin_amdgcn_mfma_f32_16x16x32_bf16(Bt[n][k], At[m][k], acc[ai][bj][m][n], 0, 0, 0); __builtin_amdgcn_s_setprio(0); } while (0)
; #define PG8_WAIT_V(n) asm volatile("s_waitcnt vmcnt(" #n ")" ::: "memory")
; #define PG8_WAIT_L(n) asm volatile("s_waitcnt lgkmcnt(" #n ")" ::: "memory")
; #define PG8_BAR __builtin_amdgcn_s_barrier()
; #define PG8_SCHED __builtin_amdgcn_sched_barrier(0)
; template <class Epi, class Sched, bool ALIGN_EPI = false, bool SP2 = false>
; __device__ __forceinline__ void gemm_phase(PG8_LAS unsigned char* lds, const Gemm g, const Sched& S, const Epi& E) {
;     ...
;         for (int t = 0; t < nt; t += 2) {
;     ...
;             PG8_LDA(At, 1, 1); PG8_STAGE(PG8_SB(1, 0), b3, voffB); PG8_STAGE(PG8_SB(1, 1), b3 + hstep, voffB); PG8_STAGE(PG8_SA(1, 0), a3, voffA);
;             PG8_WAIT_V(8); PG8_WAIT_L(0); PG8_BAR; PG8_MMA(1, 0, At, B0); PG8_MMA(1, 1, At, B1); PG8_BAR; PG8_SCHED;
	s_add_i32 s34, s34, s53
	v_lshl_add_u64 v[208:209], v[208:209], 0, s[12:13]
	s_mov_b32 m0, s34
	ds_read_b128 v[162:165], v238 offset:49152
	ds_read_b128 v[166:169], v238 offset:50176
	ds_read_b128 v[170:173], v238 offset:51200
	ds_read_b128 v[174:177], v238 offset:52224
	ds_read_b128 v[178:181], v238 offset:53248
	ds_read_b128 v[182:185], v238 offset:54272
	ds_read_b128 v[186:189], v238 offset:55296
	ds_read_b128 v[204:207], v238 offset:56320
	global_load_lds_dwordx4 v[208:209], off
	v_lshl_add_u64 v[208:209], v[210:211], 0, s[12:13]
	s_add_i32 m0, s34, 0x2000
	s_add_i32 s34, s35, s53
	global_load_lds_dwordx4 v[208:209], off
	v_lshl_add_u64 v[208:209], v[212:213], 0, s[12:13]
	s_mov_b32 m0, s34
	s_nop 0
	global_load_lds_dwordx4 v[208:209], off
	v_lshl_add_u64 v[208:209], v[214:215], 0, s[12:13]
	s_add_i32 m0, s34, 0x2000
	s_nop 0
	global_load_lds_dwordx4 v[208:209], off
	v_lshl_add_u64 v[208:209], v[216:217], 0, s[12:13]
	s_mov_b32 m0, s60
	s_nop 0
	global_load_lds_dwordx4 v[208:209], off
	v_lshl_add_u64 v[208:209], v[218:219], 0, s[12:13]
	s_mov_b32 m0, s61
	s_nop 0
	global_load_lds_dwordx4 v[208:209], off
	s_waitcnt vmcnt(8)
	s_waitcnt lgkmcnt(0)
	s_barrier
	s_waitcnt lgkmcnt(0)
	v_mfma_f32_16x16x32_bf16 v[62:65], v[66:69], v[162:165], v[62:65]
	v_mfma_f32_16x16x32_bf16 v[58:61], v[90:93], v[162:165], v[58:61]
	v_mfma_f32_16x16x32_bf16 v[46:49], v[66:69], v[170:173], v[46:49]
	v_mfma_f32_16x16x32_bf16 v[42:45], v[90:93], v[170:173], v[42:45]
	v_mfma_f32_16x16x32_bf16 v[30:33], v[66:69], v[178:181], v[30:33]
	v_mfma_f32_16x16x32_bf16 v[26:29], v[90:93], v[178:181], v[26:29]
	v_mfma_f32_16x16x32_bf16 v[14:17], v[66:69], v[186:189], v[14:17]
	v_mfma_f32_16x16x32_bf16 v[10:13], v[90:93], v[186:189], v[10:13]
	v_mfma_f32_16x16x32_bf16 v[62:65], v[78:81], v[166:169], v[62:65]
	v_mfma_f32_16x16x32_bf16 v[58:61], v[102:105], v[166:169], v[58:61]
	v_mfma_f32_16x16x32_bf16 v[46:49], v[78:81], v[174:177], v[46:49]
	v_mfma_f32_16x16x32_bf16 v[42:45], v[102:105], v[174:177], v[42:45]
	v_mfma_f32_16x16x32_bf16 v[30:33], v[78:81], v[182:185], v[30:33]
	v_mfma_f32_16x16x32_bf16 v[26:29], v[102:105], v[182:185], v[26:29]
	v_mfma_f32_16x16x32_bf16 v[14:17], v[78:81], v[204:207], v[14:17]
	v_mfma_f32_16x16x32_bf16 v[10:13], v[102:105], v[204:207], v[10:13]
	v_mfma_f32_16x16x32_bf16 v[54:57], v[114:117], v[162:165], v[54:57]
	v_mfma_f32_16x16x32_bf16 v[50:53], v[138:141], v[162:165], v[50:53]
	v_mfma_f32_16x16x32_bf16 v[38:41], v[114:117], v[170:173], v[38:41]
	v_mfma_f32_16x16x32_bf16 v[34:37], v[138:141], v[170:173], v[34:37]
	v_mfma_f32_16x16x32_bf16 v[22:25], v[114:117], v[178:181], v[22:25]
	v_mfma_f32_16x16x32_bf16 v[18:21], v[138:141], v[178:181], v[18:21]
	v_mfma_f32_16x16x32_bf16 v[6:9], v[114:117], v[186:189], v[6:9]
	v_mfma_f32_16x16x32_bf16 v[2:5], v[138:141], v[186:189], v[2:5]
	v_mfma_f32_16x16x32_bf16 v[54:57], v[126:129], v[166:169], v[54:57]
	v_mfma_f32_16x16x32_bf16 v[50:53], v[150:153], v[166:169], v[50:53]
	v_mfma_f32_16x16x32_bf16 v[38:41], v[126:129], v[174:177], v[38:41]
	v_mfma_f32_16x16x32_bf16 v[34:37], v[150:153], v[174:177], v[34:37]
	v_mfma_f32_16x16x32_bf16 v[22:25], v[126:129], v[182:185], v[22:25]
	v_mfma_f32_16x16x32_bf16 v[18:21], v[150:153], v[182:185], v[18:21]
	v_mfma_f32_16x16x32_bf16 v[6:9], v[126:129], v[204:207], v[6:9]
	v_mfma_f32_16x16x32_bf16 v[2:5], v[150:153], v[204:207], v[2:5]
	s_barrier
	s_add_u32 s38, s38, 0x100
	s_addc_u32 s39, s39, 0
	s_add_u32 s48, s48, 0x100
	s_addc_u32 s49, s49, 0
	s_cmp_ge_u32 s71, s63
	s_mov_b32 s46, s71
	s_cbranch_scc0 .LBB0_1033
	s_and_b64 vcc, exec, s[26:27]
	s_cbranch_vccz .LBB0_1036
	s_barrier

; #define PG8_STAGE(bufoff, gbase, voff) do { _Pragma("unroll") for (int _i = 0; _i < 2; ++_i) \
;         __builtin_amdgcn_global_load_lds((const unsigned*)((const char*)(gbase) + (voff)[_i]), (PG8_LAS unsigned*)(lds + (bufoff) + ldsw + _i * 8192), 16, 0, 0); } while (0)
; #define PG8_LDA(dst, b, h) do { _Pragma("unroll") for (int m = 0; m < 4; ++m) _Pragma("unroll") for (int k = 0; k < 2; ++k) dst[m][k] = *(const PG8_LAS bf16x8*)(lds + PG8_SA(b, h) + aoff + m * 2048 + k * 1024); } while (0)
; #define PG8_LDB(dst, b, h) do { _Pragma("unroll") for (int n = 0; n < 2; ++n) _Pragma("unroll") for (int k = 0; k < 2; ++k) dst[n][k] = *(const PG8_LAS bf16x8*)(lds + PG8_SB(b, h) + boff + n * 2048 + k * 1024); } while (0)
; #define PG8_WAIT_V(n) asm volatile("s_waitcnt vmcnt(" #n ")" ::: "memory")
; #define PG8_WAIT_L(n) asm volatile("s_waitcnt lgkmcnt(" #n ")" ::: "memory")
; #define PG8_BAR __builtin_amdgcn_s_barrier()
; #define PG8_SCHED __builtin_amdgcn_sched_barrier(0)
; template <class Epi, class Sched, bool ALIGN_EPI = false, bool SP2 = false>
; __device__ __forceinline__ void gemm_phase(PG8_LAS unsigned char* lds, const Gemm g, const Sched& S, const Epi& E) {
;     ...
;         const char* nA = has_next ? (const char*)g.A + (size_t)nxt.pm * tstepA + (size_t)(nxt.pn >> 2) * g.aselb : cA; const char* nB = has_next ? (const char*)g.Bt + (size_t)nxt.pn * tstep : cB;
;         for (int t = 0; t < nt; t += 2) {
;             if constexpr (Epi::MID) { if (t == (nt >> 1)) E.mid(acc, cur, wr, wc, fr, fq); }
;             const bool last = (t == nt - 2);
;             const char* a1 = cA + (size_t)(t + 1) * kstep;
;             const char* a2 = last ? nA : cA + (size_t)(t + 2) * kstep; const char* b2 = last ? nB : cB + (size_t)(t + 2) * kstep;
;             const char* a3 = a2 + kstep; const char* b3 = b2 + kstep;
;             if (last && has_next) S.a_ready(nxt);
;             if constexpr (SP2) {
;             PG8_LDB(B0, 0, 0); PG8_LDB(B1, 0, 1); PG8_SCHED; PG8_LDA(At, 0, 0); PG8_STAGE(PG8_SA(1, 1), a1 + hstepA, voffA);
;             PG8_WAIT_V(8); PG8_WAIT_L(0); PG8_BAR; PG8_MMA(0, 0, At, B0); PG8_MMA(0, 1, At, B1); PG8_BAR; PG8_SCHED;
;             PG8_LDA(At, 0, 1); PG8_STAGE(PG8_SB(0, 0), b2, voffB); PG8_STAGE(PG8_SB(0, 1), b2 + hstep, voffB); PG8_STAGE(PG8_SA(0, 0), a2, voffA);
.LBB0_1149:
	s_add_u32 s34, s46, 0xfffc0080
	s_addc_u32 s35, s47, -1
	s_add_i32 s67, 0, 0x10000
	s_cmp_eq_u32 s66, 12
	s_cselect_b32 s51, s37, s35
	s_cselect_b32 s50, s62, s34
	s_cselect_b32 s49, s27, s65
	s_cselect_b32 s48, s63, s64
	s_add_i32 s34, 0, 0x14000
	v_add_u32_e32 v156, s67, v160
	v_add_u32_e32 v163, s34, v160
	ds_read_b128 v[144:147], v156
	ds_read_b128 v[148:151], v156 offset:1024
	ds_read_b128 v[152:155], v156 offset:2048
	ds_read_b128 v[156:159], v156 offset:3072
	ds_read_b128 v[164:167], v163
	ds_read_b128 v[168:171], v163 offset:1024
	ds_read_b128 v[172:175], v163 offset:2048
	ds_read_b128 v[176:179], v163 offset:3072
	v_lshl_add_u64 v[212:213], s[46:47], 0, v[140:141]
	s_add_i32 m0, s45, 0xc000
	ds_read_b128 v[180:183], v162
	ds_read_b128 v[184:187], v162 offset:1024
	ds_read_b128 v[188:191], v162 offset:2048
	ds_read_b128 v[192:195], v162 offset:3072
	ds_read_b128 v[196:199], v162 offset:4096
	ds_read_b128 v[200:203], v162 offset:5120
	ds_read_b128 v[204:207], v162 offset:6144
	ds_read_b128 v[208:211], v162 offset:7168
	global_load_lds_dwordx4 v[212:213], off
	v_lshl_add_u64 v[212:213], s[46:47], 0, v[142:143]
	s_add_i32 m0, s45, 0xe000
	s_nop 0
	global_load_lds_dwordx4 v[212:213], off
	s_waitcnt vmcnt(8)
	s_waitcnt lgkmcnt(0)
	s_barrier
	s_waitcnt lgkmcnt(0)
	v_mfma_f32_16x16x32_bf16 v[126:129], v[144:147], v[180:183], v[126:129]
	v_mfma_f32_16x16x32_bf16 v[118:121], v[152:155], v[180:183], v[118:121]
	v_mfma_f32_16x16x32_bf16 v[110:113], v[144:147], v[188:191], v[110:113]
	v_mfma_f32_16x16x32_bf16 v[102:105], v[152:155], v[188:191], v[102:105]
	v_mfma_f32_16x16x32_bf16 v[94:97], v[144:147], v[196:199], v[94:97]
	v_mfma_f32_16x16x32_bf16 v[86:89], v[152:155], v[196:199], v[86:89]
	v_mfma_f32_16x16x32_bf16 v[78:81], v[144:147], v[204:207], v[78:81]
	v_mfma_f32_16x16x32_bf16 v[70:73], v[152:155], v[204:207], v[70:73]
	v_mfma_f32_16x16x32_bf16 v[126:129], v[148:151], v[184:187], v[126:129]
	v_mfma_f32_16x16x32_bf16 v[118:121], v[156:159], v[184:187], v[118:121]
	v_mfma_f32_16x16x32_bf16 v[110:113], v[148:151], v[192:195], v[110:113]
	v_mfma_f32_16x16x32_bf16 v[102:105], v[156:159], v[192:195], v[102:105]
	v_mfma_f32_16x16x32_bf16 v[94:97], v[148:151], v[200:203], v[94:97]
	v_mfma_f32_16x16x32_bf16 v[86:89], v[156:159], v[200:203], v[86:89]
	v_mfma_f32_16x16x32_bf16 v[78:81], v[148:151], v[208:211], v[78:81]
	v_mfma_f32_16x16x32_bf16 v[70:73], v[156:159], v[208:211], v[70:73]
	v_mfma_f32_16x16x32_bf16 v[122:125], v[164:167], v[180:183], v[122:125]
	v_mfma_f32_16x16x32_bf16 v[114:117], v[172:175], v[180:183], v[114:117]
	v_mfma_f32_16x16x32_bf16 v[106:109], v[164:167], v[188:191], v[106:109]
	v_mfma_f32_16x16x32_bf16 v[98:101], v[172:175], v[188:191], v[98:101]
	v_mfma_f32_16x16x32_bf16 v[90:93], v[164:167], v[196:199], v[90:93]
	v_mfma_f32_16x16x32_bf16 v[82:85], v[172:175], v[196:199], v[82:85]
	v_mfma_f32_16x16x32_bf16 v[74:77], v[164:167], v[204:207], v[74:77]
	v_mfma_f32_16x16x32_bf16 v[66:69], v[172:175], v[204:207], v[66:69]
	v_mfma_f32_16x16x32_bf16 v[122:125], v[168:171], v[184:187], v[122:125]
	v_mfma_f32_16x16x32_bf16 v[114:117], v[176:179], v[184:187], v[114:117]
	v_mfma_f32_16x16x32_bf16 v[106:109], v[168:171], v[192:195], v[106:109]
	v_mfma_f32_16x16x32_bf16 v[98:101], v[176:179], v[192:195], v[98:101]
	v_mfma_f32_16x16x32_bf16 v[90:93], v[168:171], v[200:203], v[90:93]
	v_mfma_f32_16x16x32_bf16 v[82:85], v[176:179], v[200:203], v[82:85]
	v_mfma_f32_16x16x32_bf16 v[74:77], v[168:171], v[208:211], v[74:77]
	v_mfma_f32_16x16x32_bf16 v[66:69], v[176:179], v[208:211], v[66:69]
	s_barrier
	s_add_i32 s35, s67, s22
	v_lshl_add_u64 v[212:213], s[48:49], 0, v[134:135]
	s_mov_b32 m0, s35
	ds_read_b128 v[180:183], v162 offset:16384
	ds_read_b128 v[184:187], v162 offset:17408
	ds_read_b128 v[188:191], v162 offset:18432
	ds_read_b128 v[192:195], v162 offset:19456
	ds_read_b128 v[196:199], v162 offset:20480
	ds_read_b128 v[200:203], v162 offset:21504
	ds_read_b128 v[204:207], v162 offset:22528
	ds_read_b128 v[208:211], v162 offset:23552
	global_load_lds_dwordx4 v[212:213], off
	s_add_i32 m0, s35, 0x2000
	s_add_u32 s68, s48, 0x40000
	v_lshl_add_u64 v[214:215], s[48:49], 0, v[130:131]
	s_addc_u32 s69, s49, 0
	s_add_i32 s34, s34, s22
	global_load_lds_dwordx4 v[214:215], off
	v_lshl_add_u64 v[216:217], s[68:69], 0, v[134:135]
	s_mov_b32 m0, s34
	v_lshl_add_u64 v[218:219], s[50:51], 0, v[132:133]
	global_load_lds_dwordx4 v[216:217], off
	v_lshl_add_u64 v[216:217], s[68:69], 0, v[130:131]
	s_add_i32 m0, s34, 0x2000
	s_nop 0
	global_load_lds_dwordx4 v[216:217], off
	v_lshl_add_u64 v[216:217], s[50:51], 0, v[136:137]
	s_mov_b32 m0, s45
	s_nop 0
	global_load_lds_dwordx4 v[216:217], off
	s_mov_b32 m0, s55
	s_nop 0
	global_load_lds_dwordx4 v[218:219], off
	s_waitcnt vmcnt(8)
	s_waitcnt lgkmcnt(0)
	s_barrier
; #define PG8_STAGE(bufoff, gbase, voff) do { _Pragma("unroll") for (int _i = 0; _i < 2; ++_i) \
;         __builtin_amdgcn_global_load_lds((const unsigned*)((const char*)(gbase) + (voff)[_i]), (PG8_LAS unsigned*)(lds + (bufoff) + ldsw + _i * 8192), 16, 0, 0); } while (0)
; #define PG8_LDA(dst, b, h) do { _Pragma("unroll") for (int m = 0; m < 4; ++m) _Pragma("unroll") for (int k = 0; k < 2; ++k) dst[m][k] = *(const PG8_LAS bf16x8*)(lds + PG8_SA(b, h) + aoff + m * 2048 + k * 1024); } while (0)
; #define PG8_LDB(dst, b, h) do { _Pragma("unroll") for (int n = 0; n < 2; ++n) _Pragma("unroll") for (int k = 0; k < 2; ++k) dst[n][k] = *(const PG8_LAS bf16x8*)(lds + PG8_SB(b, h) + boff + n * 2048 + k * 1024); } while (0)
; #define PG8_MMA(ai, bj, At, Bt) do { __builtin_amdgcn_s_setprio(1); _Pragma("unroll") for (int m = 0; m < 4; ++m) _Pragma("unroll") for (int n = 0; n < 2; ++n) _Pragma("unroll") for (int k = 0; k < 2; ++k) \
;         acc[ai][bj][m][n] = __builtin_amdgcn_mfma_f32_16x16x32_bf16(Bt[n][k], At[m][k], acc[ai][bj][m][n], 0, 0, 0); __builtin_amdgcn_s_setprio(0); } while (0)
; #define PG8_WAIT_V(n) asm volatile("s_waitcnt vmcnt(" #n ")" ::: "memory")
; #define PG8_WAIT_L(n) asm volatile("s_waitcnt lgkmcnt(" #n ")" ::: "memory")
; #define PG8_BAR __builtin_amdgcn_s_barrier()
; #define PG8_SCHED __builtin_amdgcn_sched_barrier(0)
; template <class Epi, class Sched, bool ALIGN_EPI = false, bool SP2 = false>
; __device__ __forceinline__ void gemm_phase(PG8_LAS unsigned char* lds, const Gemm g, const Sched& S, const Epi& E) {
;     ...
;             PG8_WAIT_V(8); PG8_WAIT_L(0); PG8_BAR; PG8_MMA(1, 0, At, B0); PG8_MMA(1, 1, At, B1); PG8_BAR; PG8_SCHED;
;             PG8_LDB(B0, 1, 0); PG8_LDB(B1, 1, 1); PG8_SCHED; PG8_LDA(At, 1, 0); PG8_STAGE(PG8_SA(0, 1), a2 + hstepA, voffA);
;             PG8_WAIT_V(8); PG8_WAIT_L(0); PG8_BAR; PG8_MMA(0, 0, At, B0); PG8_MMA(0, 1, At, B1); PG8_BAR; PG8_SCHED;
	s_waitcnt lgkmcnt(0)
	v_mfma_f32_16x16x32_bf16 v[62:65], v[144:147], v[180:183], v[62:65]
	v_mfma_f32_16x16x32_bf16 v[54:57], v[152:155], v[180:183], v[54:57]
	v_mfma_f32_16x16x32_bf16 v[46:49], v[144:147], v[188:191], v[46:49]
	v_mfma_f32_16x16x32_bf16 v[38:41], v[152:155], v[188:191], v[38:41]
	v_mfma_f32_16x16x32_bf16 v[30:33], v[144:147], v[196:199], v[30:33]
	v_mfma_f32_16x16x32_bf16 v[22:25], v[152:155], v[196:199], v[22:25]
	v_mfma_f32_16x16x32_bf16 v[14:17], v[144:147], v[204:207], v[14:17]
	v_mfma_f32_16x16x32_bf16 v[6:9], v[152:155], v[204:207], v[6:9]
	v_mfma_f32_16x16x32_bf16 v[62:65], v[148:151], v[184:187], v[62:65]
	v_mfma_f32_16x16x32_bf16 v[54:57], v[156:159], v[184:187], v[54:57]
	v_mfma_f32_16x16x32_bf16 v[46:49], v[148:151], v[192:195], v[46:49]
	v_mfma_f32_16x16x32_bf16 v[38:41], v[156:159], v[192:195], v[38:41]
	v_mfma_f32_16x16x32_bf16 v[30:33], v[148:151], v[200:203], v[30:33]
	v_mfma_f32_16x16x32_bf16 v[22:25], v[156:159], v[200:203], v[22:25]
	v_mfma_f32_16x16x32_bf16 v[14:17], v[148:151], v[208:211], v[14:17]
	v_mfma_f32_16x16x32_bf16 v[6:9], v[156:159], v[208:211], v[6:9]
	v_mfma_f32_16x16x32_bf16 v[58:61], v[164:167], v[180:183], v[58:61]
	v_mfma_f32_16x16x32_bf16 v[50:53], v[172:175], v[180:183], v[50:53]
	v_mfma_f32_16x16x32_bf16 v[42:45], v[164:167], v[188:191], v[42:45]
	v_mfma_f32_16x16x32_bf16 v[34:37], v[172:175], v[188:191], v[34:37]
	v_mfma_f32_16x16x32_bf16 v[26:29], v[164:167], v[196:199], v[26:29]
	v_mfma_f32_16x16x32_bf16 v[18:21], v[172:175], v[196:199], v[18:21]
	v_mfma_f32_16x16x32_bf16 v[10:13], v[164:167], v[204:207], v[10:13]
	v_mfma_f32_16x16x32_bf16 v[2:5], v[172:175], v[204:207], v[2:5]
	v_mfma_f32_16x16x32_bf16 v[58:61], v[168:171], v[184:187], v[58:61]
	v_mfma_f32_16x16x32_bf16 v[50:53], v[176:179], v[184:187], v[50:53]
	v_mfma_f32_16x16x32_bf16 v[42:45], v[168:171], v[192:195], v[42:45]
	v_mfma_f32_16x16x32_bf16 v[34:37], v[176:179], v[192:195], v[34:37]
	v_mfma_f32_16x16x32_bf16 v[26:29], v[168:171], v[200:203], v[26:29]
	v_mfma_f32_16x16x32_bf16 v[18:21], v[176:179], v[200:203], v[18:21]
	v_mfma_f32_16x16x32_bf16 v[10:13], v[168:171], v[208:211], v[10:13]
	v_mfma_f32_16x16x32_bf16 v[2:5], v[176:179], v[208:211], v[2:5]
	s_barrier
	s_add_i32 s34, 0, 0x18000
	s_add_i32 s35, 0, 0x1c000
	v_add_u32_e32 v156, s34, v160
	v_add_u32_e32 v163, s35, v160
	ds_read_b128 v[144:147], v156
	ds_read_b128 v[148:151], v156 offset:1024
	ds_read_b128 v[152:155], v156 offset:2048
	ds_read_b128 v[156:159], v156 offset:3072
	ds_read_b128 v[164:167], v163
	ds_read_b128 v[168:171], v163 offset:1024
	ds_read_b128 v[172:175], v163 offset:2048
	ds_read_b128 v[176:179], v163 offset:3072
	s_add_u32 s50, s50, 0x40000
	s_addc_u32 s51, s51, 0
	s_mov_b32 m0, s56
	v_lshl_add_u64 v[220:221], s[50:51], 0, v[136:137]
	ds_read_b128 v[180:183], v162 offset:32768
	ds_read_b128 v[184:187], v162 offset:33792
	ds_read_b128 v[188:191], v162 offset:34816
	ds_read_b128 v[192:195], v162 offset:35840
	ds_read_b128 v[196:199], v162 offset:36864
	ds_read_b128 v[200:203], v162 offset:37888
	ds_read_b128 v[204:207], v162 offset:38912
	ds_read_b128 v[208:211], v162 offset:39936
	global_load_lds_dwordx4 v[220:221], off
	v_lshl_add_u64 v[220:221], s[50:51], 0, v[132:133]
	s_mov_b32 m0, s57
	s_nop 0
	global_load_lds_dwordx4 v[220:221], off
	s_waitcnt vmcnt(8)
	s_waitcnt lgkmcnt(0)
	s_barrier
	s_waitcnt lgkmcnt(0)
	v_mfma_f32_16x16x32_bf16 v[126:129], v[144:147], v[180:183], v[126:129]
	v_mfma_f32_16x16x32_bf16 v[118:121], v[152:155], v[180:183], v[118:121]
	v_mfma_f32_16x16x32_bf16 v[110:113], v[144:147], v[188:191], v[110:113]
	v_mfma_f32_16x16x32_bf16 v[102:105], v[152:155], v[188:191], v[102:105]
	v_mfma_f32_16x16x32_bf16 v[94:97], v[144:147], v[196:199], v[94:97]
	v_mfma_f32_16x16x32_bf16 v[86:89], v[152:155], v[196:199], v[86:89]
	v_mfma_f32_16x16x32_bf16 v[78:81], v[144:147], v[204:207], v[78:81]
	v_mfma_f32_16x16x32_bf16 v[70:73], v[152:155], v[204:207], v[70:73]
	v_mfma_f32_16x16x32_bf16 v[126:129], v[148:151], v[184:187], v[126:129]
	v_mfma_f32_16x16x32_bf16 v[118:121], v[156:159], v[184:187], v[118:121]
	v_mfma_f32_16x16x32_bf16 v[110:113], v[148:151], v[192:195], v[110:113]
	v_mfma_f32_16x16x32_bf16 v[102:105], v[156:159], v[192:195], v[102:105]
	v_mfma_f32_16x16x32_bf16 v[94:97], v[148:151], v[200:203], v[94:97]
	v_mfma_f32_16x16x32_bf16 v[86:89], v[156:159], v[200:203], v[86:89]
	v_mfma_f32_16x16x32_bf16 v[78:81], v[148:151], v[208:211], v[78:81]
	v_mfma_f32_16x16x32_bf16 v[70:73], v[156:159], v[208:211], v[70:73]
	v_mfma_f32_16x16x32_bf16 v[122:125], v[164:167], v[180:183], v[122:125]
	v_mfma_f32_16x16x32_bf16 v[114:117], v[172:175], v[180:183], v[114:117]
	v_mfma_f32_16x16x32_bf16 v[106:109], v[164:167], v[188:191], v[106:109]
	v_mfma_f32_16x16x32_bf16 v[98:101], v[172:175], v[188:191], v[98:101]
	v_mfma_f32_16x16x32_bf16 v[90:93], v[164:167], v[196:199], v[90:93]
	v_mfma_f32_16x16x32_bf16 v[82:85], v[172:175], v[196:199], v[82:85]
	v_mfma_f32_16x16x32_bf16 v[74:77], v[164:167], v[204:207], v[74:77]
	v_mfma_f32_16x16x32_bf16 v[66:69], v[172:175], v[204:207], v[66:69]
	v_mfma_f32_16x16x32_bf16 v[122:125], v[168:171], v[184:187], v[122:125]
	v_mfma_f32_16x16x32_bf16 v[114:117], v[176:179], v[184:187], v[114:117]
	v_mfma_f32_16x16x32_bf16 v[106:109], v[168:171], v[192:195], v[106:109]
	v_mfma_f32_16x16x32_bf16 v[98:101], v[176:179], v[192:195], v[98:101]
	v_mfma_f32_16x16x32_bf16 v[90:93], v[168:171], v[200:203], v[90:93]
	v_mfma_f32_16x16x32_bf16 v[82:85], v[176:179], v[200:203], v[82:85]
	v_mfma_f32_16x16x32_bf16 v[74:77], v[168:171], v[208:211], v[74:77]
	v_mfma_f32_16x16x32_bf16 v[66:69], v[176:179], v[208:211], v[66:69]
	s_barrier
; #define PG8_STAGE(bufoff, gbase, voff) do { _Pragma("unroll") for (int _i = 0; _i < 2; ++_i) \
;         __builtin_amdgcn_global_load_lds((const unsigned*)((const char*)(gbase) + (voff)[_i]), (PG8_LAS unsigned*)(lds + (bufoff) + ldsw + _i * 8192), 16, 0, 0); } while (0)
; #define PG8_LDA(dst, b, h) do { _Pragma("unroll") for (int m = 0; m < 4; ++m) _Pragma("unroll") for (int k = 0; k < 2; ++k) dst[m][k] = *(const PG8_LAS bf16x8*)(lds + PG8_SA(b, h) + aoff + m * 2048 + k * 1024); } while (0)
; #define PG8_MMA(ai, bj, At, Bt) do { __builtin_amdgcn_s_setprio(1); _Pragma("unroll") for (int m = 0; m < 4; ++m) _Pragma("unroll") for (int n = 0; n < 2; ++n) _Pragma("unroll") for (int k = 0; k < 2; ++k) \
;         acc[ai][bj][m][n] = __builtin_amdgcn_mfma_f32_16x16x32_bf16(Bt[n][k], At[m][k], acc[ai][bj][m][n], 0, 0, 0); __builtin_amdgcn_s_setprio(0); } while (0)
; #define PG8_WAIT_V(n) asm volatile("s_waitcnt vmcnt(" #n ")" ::: "memory")
; #define PG8_WAIT_L(n) asm volatile("s_waitcnt lgkmcnt(" #n ")" ::: "memory")
; #define PG8_BAR __builtin_amdgcn_s_barrier()
; #define PG8_SCHED __builtin_amdgcn_sched_barrier(0)
; template <class Epi, class Sched, bool ALIGN_EPI = false, bool SP2 = false>
; __device__ __forceinline__ void gemm_phase(PG8_LAS unsigned char* lds, const Gemm g, const Sched& S, const Epi& E) {
;     ...
;             PG8_LDA(At, 1, 1); PG8_STAGE(PG8_SB(1, 0), b3, voffB); PG8_STAGE(PG8_SB(1, 1), b3 + hstep, voffB); PG8_STAGE(PG8_SA(1, 0), a3, voffA);
;             PG8_WAIT_V(8); PG8_WAIT_L(0); PG8_BAR; PG8_MMA(1, 0, At, B0); PG8_MMA(1, 1, At, B1); PG8_BAR; PG8_SCHED;
	s_add_i32 s34, s34, s22
	v_lshl_add_u64 v[212:213], v[212:213], 0, s[12:13]
	s_mov_b32 m0, s34
	ds_read_b128 v[180:183], v162 offset:49152
	ds_read_b128 v[184:187], v162 offset:50176
	ds_read_b128 v[188:191], v162 offset:51200
	ds_read_b128 v[192:195], v162 offset:52224
	ds_read_b128 v[196:199], v162 offset:53248
	ds_read_b128 v[200:203], v162 offset:54272
	ds_read_b128 v[204:207], v162 offset:55296
	ds_read_b128 v[208:211], v162 offset:56320
	global_load_lds_dwordx4 v[212:213], off
	s_add_i32 m0, s34, 0x2000
	s_add_u32 s48, s48, 0x40080
	v_lshl_add_u64 v[212:213], v[214:215], 0, s[12:13]
	s_addc_u32 s49, s49, 0
	s_add_i32 s34, s35, s22
	global_load_lds_dwordx4 v[212:213], off
	v_lshl_add_u64 v[212:213], s[48:49], 0, v[134:135]
	s_mov_b32 m0, s34
	s_nop 0
	global_load_lds_dwordx4 v[212:213], off
	v_lshl_add_u64 v[212:213], s[48:49], 0, v[130:131]
	s_add_i32 m0, s34, 0x2000
	s_nop 0
	global_load_lds_dwordx4 v[212:213], off
	v_lshl_add_u64 v[212:213], v[216:217], 0, s[12:13]
	s_mov_b32 m0, s58
	s_nop 0
	global_load_lds_dwordx4 v[212:213], off
	v_lshl_add_u64 v[212:213], v[218:219], 0, s[12:13]
	s_mov_b32 m0, s59
	s_nop 0
	global_load_lds_dwordx4 v[212:213], off
	s_waitcnt vmcnt(8)
	s_waitcnt lgkmcnt(0)
	s_barrier
	s_waitcnt lgkmcnt(0)
	v_mfma_f32_16x16x32_bf16 v[62:65], v[144:147], v[180:183], v[62:65]
	v_mfma_f32_16x16x32_bf16 v[54:57], v[152:155], v[180:183], v[54:57]
	v_mfma_f32_16x16x32_bf16 v[46:49], v[144:147], v[188:191], v[46:49]
	v_mfma_f32_16x16x32_bf16 v[38:41], v[152:155], v[188:191], v[38:41]
	v_mfma_f32_16x16x32_bf16 v[30:33], v[144:147], v[196:199], v[30:33]
	v_mfma_f32_16x16x32_bf16 v[22:25], v[152:155], v[196:199], v[22:25]
	v_mfma_f32_16x16x32_bf16 v[14:17], v[144:147], v[204:207], v[14:17]
	v_mfma_f32_16x16x32_bf16 v[6:9], v[152:155], v[204:207], v[6:9]
	v_mfma_f32_16x16x32_bf16 v[62:65], v[148:151], v[184:187], v[62:65]
	v_mfma_f32_16x16x32_bf16 v[54:57], v[156:159], v[184:187], v[54:57]
	v_mfma_f32_16x16x32_bf16 v[46:49], v[148:151], v[192:195], v[46:49]
	v_mfma_f32_16x16x32_bf16 v[38:41], v[156:159], v[192:195], v[38:41]
	v_mfma_f32_16x16x32_bf16 v[30:33], v[148:151], v[200:203], v[30:33]
	v_mfma_f32_16x16x32_bf16 v[22:25], v[156:159], v[200:203], v[22:25]
	v_mfma_f32_16x16x32_bf16 v[14:17], v[148:151], v[208:211], v[14:17]
	v_mfma_f32_16x16x32_bf16 v[6:9], v[156:159], v[208:211], v[6:9]
	v_mfma_f32_16x16x32_bf16 v[58:61], v[164:167], v[180:183], v[58:61]
	v_mfma_f32_16x16x32_bf16 v[50:53], v[172:175], v[180:183], v[50:53]
	v_mfma_f32_16x16x32_bf16 v[42:45], v[164:167], v[188:191], v[42:45]
	v_mfma_f32_16x16x32_bf16 v[34:37], v[172:175], v[188:191], v[34:37]
	v_mfma_f32_16x16x32_bf16 v[26:29], v[164:167], v[196:199], v[26:29]
	v_mfma_f32_16x16x32_bf16 v[18:21], v[172:175], v[196:199], v[18:21]
	v_mfma_f32_16x16x32_bf16 v[10:13], v[164:167], v[204:207], v[10:13]
	v_mfma_f32_16x16x32_bf16 v[2:5], v[172:175], v[204:207], v[2:5]
	v_mfma_f32_16x16x32_bf16 v[58:61], v[168:171], v[184:187], v[58:61]
	v_mfma_f32_16x16x32_bf16 v[50:53], v[176:179], v[184:187], v[50:53]
	v_mfma_f32_16x16x32_bf16 v[42:45], v[168:171], v[192:195], v[42:45]
	v_mfma_f32_16x16x32_bf16 v[34:37], v[176:179], v[192:195], v[34:37]
	v_mfma_f32_16x16x32_bf16 v[26:29], v[168:171], v[200:203], v[26:29]
	v_mfma_f32_16x16x32_bf16 v[18:21], v[176:179], v[200:203], v[18:21]
	v_mfma_f32_16x16x32_bf16 v[10:13], v[168:171], v[208:211], v[10:13]
	v_mfma_f32_16x16x32_bf16 v[2:5], v[176:179], v[208:211], v[2:5]
	s_barrier
	s_add_i32 s66, s66, 2
	s_add_u32 s46, s46, 0x100
	s_addc_u32 s47, s47, 0
	s_add_u32 s64, s64, 0x100
	s_addc_u32 s65, s65, 0
	s_cmp_gt_u32 s66, 13
	s_cbranch_scc0 .LBB0_1149
	s_and_b64 vcc, exec, s[20:21]
	s_cbranch_vccz .LBB0_1152
	s_barrier
